# v_m7 + merge/outproj: tile index remapped so the 8 column tiles of a row-block run on blocks of the same XCD (shared A tile fetched once per XCD)
# speedup vs baseline: 1.0047x; 1.0047x over previous
; DI int otid() { int t; asm volatile("v_mov_b32 %0, %1" : "=v"(t) : "v"((int)threadIdx.x)); return t; }
; #define G_LOAD(RA, RW, kt_) { _Pragma("unroll") for (int i = 0; i < 4; i++) { \
;       RA[i] = *(const u32x4*)(A + (aoff + (unsigned)(i * 32 * lda) + (unsigned)((kt_) * 64))); \
;       if (i < 2 * NI) RW[i] = *(const u32x4*)(W + (woff + (unsigned)(i * 32 * ldw) + (unsigned)((kt_) * 64))); } }
; #define G_STORE(RA, RW, buf_) { u16* dA = sA0 + (buf_) * GBUF; u16* dW = sW0 + (buf_) * GBUF; _Pragma("unroll") for (int i = 0; i < 4; i++) { \
;       *(u32x4*)(dA + (lr + i * 32) * 72 + lc * 8) = RA[i]; \
;       if (i < 2 * NI) *(u32x4*)(dW + (lr + i * 32) * 72 + lc * 8) = RW[i]; } }
; template <int NI>
; DI void gemm_core(f32x16 (&acc)[2][NI], const u16* __restrict__ A, int lda, const u16* __restrict__ W, int ldw, int K,
;                   u16* sA0, u16* sW0) {
;     ...
;   const int tid = otid(), lane = tid & 63, wv = tid >> 6, wm = wv >> 1, wn = wv & 1;
;   const int r = lane & 31, h = lane >> 5;
;   const int lc = tid & 7, lr = tid >> 3;
;   const unsigned aoff = (unsigned)(lr * lda + lc * 8);
;   const unsigned woff = (unsigned)(lr * ldw + lc * 8);
;   u32x4 raA[4], rwA[2 * NI], raB[4], rwB[2 * NI];
;     ...
;   const int nk = K >> 6;
;   G_LOAD(raA, rwA, 0)
;   G_STORE(raA, rwA, 0)
;   G_LOAD(raA, rwA, 1)
;   if (nk > 2) G_LOAD(raB, rwB, 2)
;   __syncthreads();
; DI void phase_outproj(const Params& p, int l, int half, char* smem) {
;     ...
;   for (int it = blockIdx.x; it < ntiles; it += gridDim.x) {
;     int tmi = it >> 3, tn = it & 7;
;     int bb = tmi / nq, qb = tmi % nq + (34 - nq);
;     long mh0 = (long)bb * T + qb * 128;
;     int b = half * HB + bb;
;     f32x16 acc[2][2];
;     zero_acc<2>(acc);
;     gemm_core<2>(acc, p.ybuf + mh0 * DM, DM, p.Wt_out + ((long)l * 1024 + tn * 128) * 1024, 1024, 1024, sA, sW);
.LBB0_41:
	s_and_b32 s0, s56, 7
	s_bfe_u32 s12, s56, 0x30006
	s_lshl_b32 s12, s12, 3
	s_add_i32 s0, s0, s12
	s_lshr_b32 s12, s56, 9
	s_lshl_b32 s12, s12, 6
	s_add_i32 s0, s0, s12
	s_abs_i32 s12, s0
	s_mul_hi_u32 s13, s12, s55
	s_mul_i32 s21, s13, s50
	s_sub_i32 s12, s12, s21
	s_ashr_i32 s1, s56, 31
	s_add_i32 s21, s13, 1
	s_sub_i32 s26, s12, s50
	s_cmp_ge_u32 s12, s50
	s_cselect_b32 s13, s21, s13
	s_cselect_b32 s12, s26, s12
	s_add_i32 s21, s13, 1
	s_cmp_ge_u32 s12, s50
	s_cselect_b32 s12, s21, s13
	s_xor_b32 s12, s12, s1
	s_sub_i32 s12, s12, s1
	s_mul_i32 s1, s12, s50
	s_sub_i32 s0, s0, s1
	s_sub_i32 s26, s0, s50
	s_lshl_b32 s57, s26, 7
	s_addk_i32 s57, 0x1100
	s_mul_i32 s1, s12, 0x1100
	s_ashr_i32 s13, s57, 31
	s_mul_hi_i32 s0, s12, 0x1100
	s_add_u32 s40, s1, s57
	s_addc_u32 s41, s0, s13
	s_lshl_b64 s[0:1], s[40:41], 11
	s_add_u32 s0, s62, s0
	v_mov_b32 v81, v198
	s_addc_u32 s1, s63, s1
	v_lshlrev_b32_e32 v0, 3, v81
	s_bfe_u32 s13, s56, 0x30003
	s_lshl_b32 s13, s13, 7
	v_ashrrev_i32_e32 v82, 3, v81
	v_and_b32_e32 v89, 56, v0
	s_and_b32 s48, s13, 0x380
	v_lshl_or_b32 v176, v82, 10, v89
	s_lshl_b32 s13, s48, 11
	s_waitcnt vmcnt(2)
	v_lshlrev_b64 v[4:5], 1, v[176:177]
	s_waitcnt vmcnt(1)
	v_add_u32_e32 v8, 0x8000, v176
	v_mov_b32_e32 v9, v177
	s_add_u32 s36, s53, s13
	v_lshl_add_u64 v[86:87], s[0:1], 0, v[4:5]
	s_waitcnt vmcnt(0)
	v_lshlrev_b64 v[12:13], 1, v[8:9]
	v_add_u32_e32 v16, 0x10000, v176
	v_mov_b32_e32 v17, v177
	v_add_u32_e32 v20, 0x18000, v176
	v_mov_b32_e32 v21, v177
	s_addc_u32 s37, s54, 0
	global_load_dwordx4 v[0:3], v[86:87], off
	v_lshl_add_u64 v[8:9], s[0:1], 0, v[12:13]
	v_lshlrev_b64 v[24:25], 1, v[16:17]
	v_lshlrev_b64 v[28:29], 1, v[20:21]
	v_lshl_add_u64 v[84:85], s[36:37], 0, v[4:5]
	global_load_dwordx4 v[8:11], v[8:9], off
	v_lshl_add_u64 v[12:13], s[36:37], 0, v[12:13]
	v_lshl_add_u64 v[16:17], s[0:1], 0, v[24:25]
	v_lshl_add_u64 v[20:21], s[0:1], 0, v[28:29]
	v_lshl_add_u64 v[24:25], s[36:37], 0, v[24:25]
	v_lshl_add_u64 v[28:29], s[36:37], 0, v[28:29]
	global_load_dwordx4 v[4:7], v[84:85], off
	v_add_u32_e32 v40, 0x8040, v176
	global_load_dwordx4 v[12:15], v[12:13], off
	v_mov_b32_e32 v41, v177
	global_load_dwordx4 v[16:19], v[16:17], off
	v_lshlrev_b64 v[44:45], 1, v[40:41]
	global_load_dwordx4 v[20:23], v[20:21], off
	v_lshl_add_u64 v[40:41], s[0:1], 0, v[44:45]
	global_load_dwordx4 v[24:27], v[24:25], off
	s_nop 0
	global_load_dwordx4 v[28:31], v[28:29], off
	s_nop 0
	global_load_dwordx4 v[32:35], v[86:87], off offset:128
	global_load_dwordx4 v[36:39], v[84:85], off offset:128
	v_add_u32_e32 v48, 0x10040, v176
	v_mov_b32_e32 v49, v177
	global_load_dwordx4 v[40:43], v[40:41], off
	v_lshl_add_u64 v[44:45], s[36:37], 0, v[44:45]
	v_lshlrev_b64 v[52:53], 1, v[48:49]
	global_load_dwordx4 v[44:47], v[44:45], off
	v_lshl_add_u64 v[48:49], s[0:1], 0, v[52:53]
	v_add_u32_e32 v56, 0x18040, v176
	v_mov_b32_e32 v57, v177
	global_load_dwordx4 v[48:51], v[48:49], off
	v_lshl_add_u64 v[52:53], s[36:37], 0, v[52:53]
	v_lshlrev_b64 v[60:61], 1, v[56:57]
	global_load_dwordx4 v[52:55], v[52:53], off
	v_lshl_add_u64 v[56:57], s[0:1], 0, v[60:61]
	global_load_dwordx4 v[56:59], v[56:57], off
	v_lshl_add_u64 v[60:61], s[36:37], 0, v[60:61]
	global_load_dwordx4 v[60:63], v[60:61], off
	v_mul_lo_u32 v82, v82, s23
	v_mov_b32_e32 v83, v177
	v_lshl_add_u32 v89, v89, 1, v82
	v_add_u32_e32 v82, 0x8080, v176
	v_lshlrev_b64 v[82:83], 1, v[82:83]
	v_mov_b32_e32 v91, v177
	v_add_u32_e32 v90, 0x10080, v176
	v_lshl_add_u64 v[96:97], s[0:1], 0, v[82:83]
	global_load_dwordx4 v[92:95], v[86:87], off offset:256
	s_nop 0
	global_load_dwordx4 v[96:99], v[96:97], off
	v_lshl_add_u64 v[82:83], s[36:37], 0, v[82:83]
	global_load_dwordx4 v[100:103], v[84:85], off offset:256
	global_load_dwordx4 v[104:107], v[82:83], off
	v_and_b32_e32 v124, 31, v81
	s_mov_b64 s[46:47], -1
	s_and_b64 vcc, exec, s[38:39]
	s_waitcnt vmcnt(19)
	ds_write_b128 v89, v[0:3]
	s_waitcnt vmcnt(18)
	ds_write_b128 v89, v[8:11] offset:4608
	s_waitcnt vmcnt(15)
	ds_write_b128 v89, v[16:19] offset:9216
	s_waitcnt vmcnt(14)
	ds_write_b128 v89, v[20:23] offset:13824
	ds_write_b128 v89, v[4:7] offset:18432
	ds_write_b128 v89, v[12:15] offset:23040
	s_waitcnt vmcnt(13)
	ds_write_b128 v89, v[24:27] offset:27648
	s_waitcnt vmcnt(12)
	ds_write_b128 v89, v[28:31] offset:32256
	v_lshlrev_b64 v[0:1], 1, v[90:91]
	v_lshl_add_u64 v[2:3], s[0:1], 0, v[0:1]
	v_lshl_add_u64 v[0:1], s[36:37], 0, v[0:1]
	global_load_dwordx4 v[112:115], v[0:1], off
	v_add_u32_e32 v0, 0x18080, v176
	v_mov_b32_e32 v1, v177
	v_lshlrev_b64 v[0:1], 1, v[0:1]
	global_load_dwordx4 v[108:111], v[2:3], off
	v_lshl_add_u64 v[2:3], s[0:1], 0, v[0:1]
	v_lshl_add_u64 v[0:1], s[36:37], 0, v[0:1]
	global_load_dwordx4 v[120:123], v[0:1], off
	v_lshrrev_b32_e32 v0, 1, v81
	v_and_or_b32 v1, v0, s22, v124
	v_and_b32_e32 v4, 16, v0
	global_load_dwordx4 v[116:119], v[2:3], off
	s_waitcnt lgkmcnt(0)
	s_barrier
; #define G_LOAD(RA, RW, kt_) { _Pragma("unroll") for (int i = 0; i < 4; i++) { \
;       RA[i] = *(const u32x4*)(A + (aoff + (unsigned)(i * 32 * lda) + (unsigned)((kt_) * 64))); \
;       if (i < 2 * NI) RW[i] = *(const u32x4*)(W + (woff + (unsigned)(i * 32 * ldw) + (unsigned)((kt_) * 64))); } }
; #define G_STORE(RA, RW, buf_) { u16* dA = sA0 + (buf_) * GBUF; u16* dW = sW0 + (buf_) * GBUF; _Pragma("unroll") for (int i = 0; i < 4; i++) { \
;       *(u32x4*)(dA + (lr + i * 32) * 72 + lc * 8) = RA[i]; \
;       if (i < 2 * NI) *(u32x4*)(dW + (lr + i * 32) * 72 + lc * 8) = RW[i]; } }
; template <int NI>
; DI void gemm_core(f32x16 (&acc)[2][NI], const u16* __restrict__ A, int lda, const u16* __restrict__ W, int ldw, int K,
;                   u16* sA0, u16* sW0) {
;     ...
;   const int nk = K >> 6;
;   G_LOAD(raA, rwA, 0)
;   G_STORE(raA, rwA, 0)
;   G_LOAD(raA, rwA, 1)
;   if (nk > 2) G_LOAD(raB, rwB, 2)
;   __syncthreads();
;   for (int kt = 0; kt < nk; kt += 2) {
;     G_STORE(raA, rwA, 1)
;     if (kt + 3 < nk) G_LOAD(raA, rwA, kt + 3)
;     G_COMPUTE(0)
;     __syncthreads();
;     if (kt + 2 < nk) G_STORE(raB, rwB, 0)
;     if (kt + 4 < nk) G_LOAD(raB, rwB, kt + 4)
;     G_COMPUTE(1)
;     __syncthreads();
	v_add_u32_e32 v90, 0xd800, v89
	v_mad_u64_u32 v[82:83], s[42:43], v1, s23, v[4:5]
	s_waitcnt vmcnt(15)
	ds_write_b128 v89, v[32:35] offset:36864
	s_waitcnt vmcnt(14)
	ds_write_b128 v89, v[36:39] offset:55296
	s_waitcnt vmcnt(13)
	ds_write_b128 v89, v[40:43] offset:41472
	s_waitcnt vmcnt(12)
	ds_write_b128 v89, v[44:47] offset:59904
	s_waitcnt vmcnt(11)
	ds_write_b128 v89, v[48:51] offset:46080
	s_waitcnt vmcnt(10)
	ds_write_b128 v89, v[52:55] offset:64512
	s_waitcnt vmcnt(9)
	ds_write_b128 v89, v[56:59] offset:50688
	s_waitcnt vmcnt(8)
	ds_write_b128 v90, v[60:63] offset:13824
	ds_read_b128 v[0:3], v82
	v_and_b32_e32 v5, 0x5f, v81
	v_mad_u32_u24 v81, v5, s23, v4
	ds_read_b128 v[4:7], v81 offset:18432
	ds_read_b128 v[124:127], v82 offset:32
	ds_read_b128 v[128:131], v81 offset:18464
	ds_read_b128 v[16:19], v81 offset:23040
	ds_read_b128 v[132:135], v81 offset:23072
	s_waitcnt lgkmcnt(4)
	v_mfma_f32_32x32x16_bf16 v[32:47], v[0:3], v[4:7], 0
	ds_read_b128 v[20:23], v82 offset:4608
	ds_read_b128 v[136:139], v82 offset:4640
	s_waitcnt lgkmcnt(3)
	v_mfma_f32_32x32x16_bf16 v[48:63], v[0:3], v[16:19], 0
	s_waitcnt lgkmcnt(1)
	v_mfma_f32_32x32x16_bf16 v[0:15], v[20:23], v[4:7], 0
	v_mfma_f32_32x32x16_bf16 v[16:31], v[20:23], v[16:19], 0
	v_mfma_f32_32x32x16_bf16 v[32:47], v[124:127], v[128:131], v[32:47]
	v_mfma_f32_32x32x16_bf16 v[48:63], v[124:127], v[132:135], v[48:63]
	s_waitcnt lgkmcnt(0)
	v_mfma_f32_32x32x16_bf16 v[0:15], v[136:139], v[128:131], v[0:15]
	v_mfma_f32_32x32x16_bf16 v[16:31], v[136:139], v[132:135], v[16:31]
	ds_read_b128 v[124:127], v82 offset:64
	ds_read_b128 v[128:131], v81 offset:18496
	ds_read_b128 v[132:135], v82 offset:96
	ds_read_b128 v[136:139], v81 offset:18528
	ds_read_b128 v[140:143], v81 offset:23104
	ds_read_b128 v[144:147], v81 offset:23136
	s_waitcnt lgkmcnt(4)
	v_mfma_f32_32x32x16_bf16 v[32:47], v[124:127], v[128:131], v[32:47]
	s_waitcnt lgkmcnt(1)
	v_mfma_f32_32x32x16_bf16 v[48:63], v[124:127], v[140:143], v[48:63]
	ds_read_b128 v[124:127], v82 offset:4672
	ds_read_b128 v[148:151], v82 offset:4704
	s_waitcnt lgkmcnt(1)
	v_mfma_f32_32x32x16_bf16 v[0:15], v[124:127], v[128:131], v[0:15]
	v_mfma_f32_32x32x16_bf16 v[16:31], v[124:127], v[140:143], v[16:31]
	v_add_u32_e32 v140, 0x80c0, v176
	v_mov_b32_e32 v141, v177
	global_load_dwordx4 v[124:127], v[86:87], off offset:384
	global_load_dwordx4 v[128:131], v[84:85], off offset:384
	v_lshlrev_b64 v[152:153], 1, v[140:141]
	v_lshl_add_u64 v[140:141], s[0:1], 0, v[152:153]
	global_load_dwordx4 v[140:143], v[140:141], off
	v_lshl_add_u64 v[152:153], s[36:37], 0, v[152:153]
	v_mfma_f32_32x32x16_bf16 v[32:47], v[132:135], v[136:139], v[32:47]
	global_load_dwordx4 v[152:155], v[152:153], off
	v_mfma_f32_32x32x16_bf16 v[48:63], v[132:135], v[144:147], v[48:63]
	v_add_u32_e32 v132, 0x100c0, v176
	v_mov_b32_e32 v133, v177
	v_lshlrev_b64 v[156:157], 1, v[132:133]
	v_lshl_add_u64 v[132:133], s[0:1], 0, v[156:157]
	global_load_dwordx4 v[132:135], v[132:133], off
	v_lshl_add_u64 v[156:157], s[36:37], 0, v[156:157]
	global_load_dwordx4 v[156:159], v[156:157], off
	s_waitcnt lgkmcnt(0)
	v_mfma_f32_32x32x16_bf16 v[0:15], v[148:151], v[136:139], v[0:15]
	v_add_u32_e32 v136, 0x180c0, v176
	v_mov_b32_e32 v137, v177
	v_lshlrev_b64 v[160:161], 1, v[136:137]
	v_lshl_add_u64 v[136:137], s[0:1], 0, v[160:161]
	global_load_dwordx4 v[136:139], v[136:137], off
	v_lshl_add_u64 v[160:161], s[36:37], 0, v[160:161]
	global_load_dwordx4 v[160:163], v[160:161], off
	s_barrier
	s_waitcnt vmcnt(15)
	ds_write_b128 v89, v[92:95]
	s_waitcnt vmcnt(13)
	ds_write_b128 v89, v[100:103] offset:18432
	ds_write_b128 v89, v[96:99] offset:4608
	s_waitcnt vmcnt(12)
	ds_write_b128 v89, v[104:107] offset:23040
	s_waitcnt vmcnt(10)
	ds_write_b128 v89, v[108:111] offset:9216
	ds_write_b128 v89, v[112:115] offset:27648
	s_waitcnt vmcnt(8)
	ds_write_b128 v89, v[116:119] offset:13824
	ds_write_b128 v89, v[120:123] offset:32256
	v_mfma_f32_32x32x16_bf16 v[16:31], v[148:151], v[144:147], v[16:31]
	ds_read_b128 v[92:95], v82 offset:36864
	ds_read_b128 v[96:99], v81 offset:55296
	ds_read_b128 v[100:103], v82 offset:36896
	ds_read_b128 v[104:107], v81 offset:55328
	ds_read_b128 v[108:111], v81 offset:59904
	ds_read_b128 v[112:115], v81 offset:59936
	s_waitcnt lgkmcnt(4)
	v_mfma_f32_32x32x16_bf16 v[32:47], v[92:95], v[96:99], v[32:47]
	s_waitcnt lgkmcnt(1)
	v_mfma_f32_32x32x16_bf16 v[48:63], v[92:95], v[108:111], v[48:63]
	ds_read_b128 v[92:95], v82 offset:41472
	ds_read_b128 v[116:119], v82 offset:41504
	s_waitcnt lgkmcnt(1)
	v_mfma_f32_32x32x16_bf16 v[0:15], v[92:95], v[96:99], v[0:15]
	v_mfma_f32_32x32x16_bf16 v[16:31], v[92:95], v[108:111], v[16:31]
	v_mfma_f32_32x32x16_bf16 v[32:47], v[100:103], v[104:107], v[32:47]
	v_mfma_f32_32x32x16_bf16 v[48:63], v[100:103], v[112:115], v[48:63]
	s_waitcnt lgkmcnt(0)
	v_mfma_f32_32x32x16_bf16 v[0:15], v[116:119], v[104:107], v[0:15]
	ds_read_b128 v[92:95], v82 offset:36928
	ds_read_b128 v[96:99], v81 offset:55360
	ds_read_b128 v[100:103], v82 offset:36960
	ds_read_b128 v[104:107], v81 offset:55392
	v_mfma_f32_32x32x16_bf16 v[16:31], v[116:119], v[112:115], v[16:31]
	ds_read_b128 v[108:111], v81 offset:59968
	ds_read_b128 v[112:115], v81 offset:60000
	s_waitcnt lgkmcnt(4)
	v_mfma_f32_32x32x16_bf16 v[32:47], v[92:95], v[96:99], v[32:47]
	s_waitcnt lgkmcnt(1)
	v_mfma_f32_32x32x16_bf16 v[48:63], v[92:95], v[108:111], v[48:63]
	ds_read_b128 v[92:95], v82 offset:41536
	ds_read_b128 v[116:119], v82 offset:41568
	s_waitcnt lgkmcnt(1)
	v_mfma_f32_32x32x16_bf16 v[0:15], v[92:95], v[96:99], v[0:15]
	v_mfma_f32_32x32x16_bf16 v[16:31], v[92:95], v[108:111], v[16:31]
	v_add_u32_e32 v108, 0x8100, v176
	v_mov_b32_e32 v109, v177
	global_load_dwordx4 v[92:95], v[86:87], off offset:512
	global_load_dwordx4 v[96:99], v[84:85], off offset:512
	v_lshlrev_b64 v[120:121], 1, v[108:109]
	v_lshl_add_u64 v[108:109], s[0:1], 0, v[120:121]
	global_load_dwordx4 v[108:111], v[108:109], off
	v_lshl_add_u64 v[120:121], s[36:37], 0, v[120:121]
	v_mfma_f32_32x32x16_bf16 v[32:47], v[100:103], v[104:107], v[32:47]
	global_load_dwordx4 v[120:123], v[120:121], off
	v_mfma_f32_32x32x16_bf16 v[48:63], v[100:103], v[112:115], v[48:63]
	v_add_u32_e32 v100, 0x10100, v176
	v_mov_b32_e32 v101, v177
	v_lshlrev_b64 v[144:145], 1, v[100:101]
	v_lshl_add_u64 v[100:101], s[0:1], 0, v[144:145]
	global_load_dwordx4 v[100:103], v[100:101], off
	v_lshl_add_u64 v[144:145], s[36:37], 0, v[144:145]
	global_load_dwordx4 v[144:147], v[144:145], off
	s_waitcnt lgkmcnt(0)
	v_mfma_f32_32x32x16_bf16 v[0:15], v[116:119], v[104:107], v[0:15]
	v_add_u32_e32 v104, 0x18100, v176
	v_mov_b32_e32 v105, v177
	v_lshlrev_b64 v[148:149], 1, v[104:105]
	v_lshl_add_u64 v[104:105], s[0:1], 0, v[148:149]
	v_lshl_add_u64 v[148:149], s[36:37], 0, v[148:149]
	global_load_dwordx4 v[104:107], v[104:105], off
	s_nop 0
	global_load_dwordx4 v[148:151], v[148:149], off
	s_barrier
; #define G_LOAD(RA, RW, kt_) { _Pragma("unroll") for (int i = 0; i < 4; i++) { \
;       RA[i] = *(const u32x4*)(A + (aoff + (unsigned)(i * 32 * lda) + (unsigned)((kt_) * 64))); \
;       if (i < 2 * NI) RW[i] = *(const u32x4*)(W + (woff + (unsigned)(i * 32 * ldw) + (unsigned)((kt_) * 64))); } }
; #define G_STORE(RA, RW, buf_) { u16* dA = sA0 + (buf_) * GBUF; u16* dW = sW0 + (buf_) * GBUF; _Pragma("unroll") for (int i = 0; i < 4; i++) { \
;       *(u32x4*)(dA + (lr + i * 32) * 72 + lc * 8) = RA[i]; \
;       if (i < 2 * NI) *(u32x4*)(dW + (lr + i * 32) * 72 + lc * 8) = RW[i]; } }
; template <int NI>
; DI void gemm_core(f32x16 (&acc)[2][NI], const u16* __restrict__ A, int lda, const u16* __restrict__ W, int ldw, int K,
;                   u16* sA0, u16* sW0) {
;     ...
;   const int nk = K >> 6;
;   G_LOAD(raA, rwA, 0)
;   G_STORE(raA, rwA, 0)
;   G_LOAD(raA, rwA, 1)
;   if (nk > 2) G_LOAD(raB, rwB, 2)
;   __syncthreads();
;   for (int kt = 0; kt < nk; kt += 2) {
;     G_STORE(raA, rwA, 1)
;     if (kt + 3 < nk) G_LOAD(raA, rwA, kt + 3)
;     G_COMPUTE(0)
;     __syncthreads();
;     if (kt + 2 < nk) G_STORE(raB, rwB, 0)
;     if (kt + 4 < nk) G_LOAD(raB, rwB, kt + 4)
;     G_COMPUTE(1)
;     __syncthreads();
	s_waitcnt vmcnt(15)
	ds_write_b128 v89, v[124:127] offset:36864
	s_waitcnt vmcnt(14)
	ds_write_b128 v89, v[128:131] offset:55296
	s_waitcnt vmcnt(13)
	ds_write_b128 v89, v[140:143] offset:41472
	s_waitcnt vmcnt(12)
	ds_write_b128 v89, v[152:155] offset:59904
	s_waitcnt vmcnt(11)
	ds_write_b128 v89, v[132:135] offset:46080
	s_waitcnt vmcnt(10)
	ds_write_b128 v89, v[156:159] offset:64512
	s_waitcnt vmcnt(9)
	ds_write_b128 v89, v[136:139] offset:50688
	s_waitcnt vmcnt(8)
	ds_write_b128 v90, v[160:163] offset:13824
	v_mfma_f32_32x32x16_bf16 v[16:31], v[116:119], v[112:115], v[16:31]
	ds_read_b128 v[112:115], v82
	ds_read_b128 v[116:119], v81 offset:18432
	ds_read_b128 v[124:127], v82 offset:32
	ds_read_b128 v[128:131], v81 offset:18464
	ds_read_b128 v[132:135], v81 offset:23040
	ds_read_b128 v[136:139], v81 offset:23072
	s_waitcnt lgkmcnt(4)
	v_mfma_f32_32x32x16_bf16 v[32:47], v[112:115], v[116:119], v[32:47]
	s_waitcnt lgkmcnt(1)
	v_mfma_f32_32x32x16_bf16 v[48:63], v[112:115], v[132:135], v[48:63]
	ds_read_b128 v[112:115], v82 offset:4608
	ds_read_b128 v[140:143], v82 offset:4640
	s_waitcnt lgkmcnt(1)
	v_mfma_f32_32x32x16_bf16 v[0:15], v[112:115], v[116:119], v[0:15]
	v_mfma_f32_32x32x16_bf16 v[16:31], v[112:115], v[132:135], v[16:31]
	v_mfma_f32_32x32x16_bf16 v[32:47], v[124:127], v[128:131], v[32:47]
	v_mfma_f32_32x32x16_bf16 v[48:63], v[124:127], v[136:139], v[48:63]
	s_waitcnt lgkmcnt(0)
	v_mfma_f32_32x32x16_bf16 v[0:15], v[140:143], v[128:131], v[0:15]
	ds_read_b128 v[112:115], v82 offset:64
	ds_read_b128 v[116:119], v81 offset:18496
	ds_read_b128 v[124:127], v82 offset:96
	ds_read_b128 v[128:131], v81 offset:18528
	v_mfma_f32_32x32x16_bf16 v[16:31], v[140:143], v[136:139], v[16:31]
	ds_read_b128 v[132:135], v81 offset:23104
	ds_read_b128 v[136:139], v81 offset:23136
	s_waitcnt lgkmcnt(4)
	v_mfma_f32_32x32x16_bf16 v[32:47], v[112:115], v[116:119], v[32:47]
	s_waitcnt lgkmcnt(1)
	v_mfma_f32_32x32x16_bf16 v[48:63], v[112:115], v[132:135], v[48:63]
	ds_read_b128 v[112:115], v82 offset:4672
	ds_read_b128 v[140:143], v82 offset:4704
	s_waitcnt lgkmcnt(1)
	v_mfma_f32_32x32x16_bf16 v[0:15], v[112:115], v[116:119], v[0:15]
	v_mfma_f32_32x32x16_bf16 v[16:31], v[112:115], v[132:135], v[16:31]
	v_add_u32_e32 v132, 0x8140, v176
	v_mov_b32_e32 v133, v177
	global_load_dwordx4 v[112:115], v[86:87], off offset:640
	global_load_dwordx4 v[116:119], v[84:85], off offset:640
	v_lshlrev_b64 v[152:153], 1, v[132:133]
	v_lshl_add_u64 v[132:133], s[0:1], 0, v[152:153]
	global_load_dwordx4 v[132:135], v[132:133], off
	v_lshl_add_u64 v[152:153], s[36:37], 0, v[152:153]
	v_mfma_f32_32x32x16_bf16 v[32:47], v[124:127], v[128:131], v[32:47]
	global_load_dwordx4 v[152:155], v[152:153], off
	v_mfma_f32_32x32x16_bf16 v[48:63], v[124:127], v[136:139], v[48:63]
	v_add_u32_e32 v124, 0x10140, v176
	v_mov_b32_e32 v125, v177
	v_lshlrev_b64 v[156:157], 1, v[124:125]
	v_lshl_add_u64 v[124:125], s[0:1], 0, v[156:157]
	global_load_dwordx4 v[124:127], v[124:125], off
	v_lshl_add_u64 v[156:157], s[36:37], 0, v[156:157]
	global_load_dwordx4 v[156:159], v[156:157], off
	s_waitcnt lgkmcnt(0)
	v_mfma_f32_32x32x16_bf16 v[0:15], v[140:143], v[128:131], v[0:15]
	v_add_u32_e32 v128, 0x18140, v176
	v_mov_b32_e32 v129, v177
	v_lshlrev_b64 v[160:161], 1, v[128:129]
	v_lshl_add_u64 v[128:129], s[0:1], 0, v[160:161]
	global_load_dwordx4 v[128:131], v[128:129], off
	v_lshl_add_u64 v[160:161], s[36:37], 0, v[160:161]
	global_load_dwordx4 v[160:163], v[160:161], off
	s_barrier
	s_waitcnt vmcnt(15)
	ds_write_b128 v89, v[92:95]
	s_waitcnt vmcnt(14)
	ds_write_b128 v89, v[96:99] offset:18432
	s_waitcnt vmcnt(13)
	ds_write_b128 v89, v[108:111] offset:4608
	s_waitcnt vmcnt(12)
	ds_write_b128 v89, v[120:123] offset:23040
	s_waitcnt vmcnt(11)
	ds_write_b128 v89, v[100:103] offset:9216
	s_waitcnt vmcnt(10)
	ds_write_b128 v89, v[144:147] offset:27648
	s_waitcnt vmcnt(9)
	ds_write_b128 v89, v[104:107] offset:13824
	s_waitcnt vmcnt(8)
	ds_write_b128 v89, v[148:151] offset:32256
	v_mfma_f32_32x32x16_bf16 v[16:31], v[140:143], v[136:139], v[16:31]
	ds_read_b128 v[92:95], v82 offset:36864
	ds_read_b128 v[96:99], v81 offset:55296
	ds_read_b128 v[100:103], v82 offset:36896
	ds_read_b128 v[104:107], v81 offset:55328
	ds_read_b128 v[108:111], v81 offset:59904
	ds_read_b128 v[120:123], v81 offset:59936
	s_waitcnt lgkmcnt(4)
	v_mfma_f32_32x32x16_bf16 v[32:47], v[92:95], v[96:99], v[32:47]
	s_waitcnt lgkmcnt(1)
	v_mfma_f32_32x32x16_bf16 v[48:63], v[92:95], v[108:111], v[48:63]
	ds_read_b128 v[92:95], v82 offset:41472
	ds_read_b128 v[136:139], v82 offset:41504
	s_waitcnt lgkmcnt(1)
	v_mfma_f32_32x32x16_bf16 v[0:15], v[92:95], v[96:99], v[0:15]
	v_mfma_f32_32x32x16_bf16 v[16:31], v[92:95], v[108:111], v[16:31]
	v_mfma_f32_32x32x16_bf16 v[32:47], v[100:103], v[104:107], v[32:47]
	v_mfma_f32_32x32x16_bf16 v[48:63], v[100:103], v[120:123], v[48:63]
	s_waitcnt lgkmcnt(0)
	v_mfma_f32_32x32x16_bf16 v[0:15], v[136:139], v[104:107], v[0:15]
	ds_read_b128 v[92:95], v82 offset:36928
	ds_read_b128 v[96:99], v81 offset:55360
	ds_read_b128 v[100:103], v82 offset:36960
	ds_read_b128 v[104:107], v81 offset:55392
	v_mfma_f32_32x32x16_bf16 v[16:31], v[136:139], v[120:123], v[16:31]
	ds_read_b128 v[108:111], v81 offset:59968
	ds_read_b128 v[120:123], v81 offset:60000
	s_waitcnt lgkmcnt(4)
	v_mfma_f32_32x32x16_bf16 v[32:47], v[92:95], v[96:99], v[32:47]
	s_waitcnt lgkmcnt(1)
	v_mfma_f32_32x32x16_bf16 v[48:63], v[92:95], v[108:111], v[48:63]
	ds_read_b128 v[92:95], v82 offset:41536
	ds_read_b128 v[136:139], v82 offset:41568
	s_waitcnt lgkmcnt(1)
	v_mfma_f32_32x32x16_bf16 v[0:15], v[92:95], v[96:99], v[0:15]
	v_mfma_f32_32x32x16_bf16 v[16:31], v[92:95], v[108:111], v[16:31]
	v_add_u32_e32 v108, 0x8180, v176
	v_mov_b32_e32 v109, v177
	global_load_dwordx4 v[92:95], v[86:87], off offset:768
	global_load_dwordx4 v[96:99], v[84:85], off offset:768
	v_lshlrev_b64 v[140:141], 1, v[108:109]
	v_lshl_add_u64 v[108:109], s[0:1], 0, v[140:141]
	global_load_dwordx4 v[108:111], v[108:109], off
	v_lshl_add_u64 v[140:141], s[36:37], 0, v[140:141]
	v_mfma_f32_32x32x16_bf16 v[32:47], v[100:103], v[104:107], v[32:47]
	global_load_dwordx4 v[140:143], v[140:141], off
	v_mfma_f32_32x32x16_bf16 v[48:63], v[100:103], v[120:123], v[48:63]
	v_add_u32_e32 v100, 0x10180, v176
	v_mov_b32_e32 v101, v177
	v_lshlrev_b64 v[144:145], 1, v[100:101]
	v_lshl_add_u64 v[100:101], s[0:1], 0, v[144:145]
	global_load_dwordx4 v[100:103], v[100:101], off
	v_lshl_add_u64 v[144:145], s[36:37], 0, v[144:145]
	global_load_dwordx4 v[144:147], v[144:145], off
	s_waitcnt lgkmcnt(0)
	v_mfma_f32_32x32x16_bf16 v[0:15], v[136:139], v[104:107], v[0:15]
	v_add_u32_e32 v104, 0x18180, v176
	v_mov_b32_e32 v105, v177
	v_lshlrev_b64 v[148:149], 1, v[104:105]
	v_lshl_add_u64 v[104:105], s[0:1], 0, v[148:149]
	v_lshl_add_u64 v[148:149], s[36:37], 0, v[148:149]
	global_load_dwordx4 v[104:107], v[104:105], off
	s_nop 0
	global_load_dwordx4 v[148:151], v[148:149], off
	s_barrier
; #define G_LOAD(RA, RW, kt_) { _Pragma("unroll") for (int i = 0; i < 4; i++) { \
;       RA[i] = *(const u32x4*)(A + (aoff + (unsigned)(i * 32 * lda) + (unsigned)((kt_) * 64))); \
;       if (i < 2 * NI) RW[i] = *(const u32x4*)(W + (woff + (unsigned)(i * 32 * ldw) + (unsigned)((kt_) * 64))); } }
; #define G_STORE(RA, RW, buf_) { u16* dA = sA0 + (buf_) * GBUF; u16* dW = sW0 + (buf_) * GBUF; _Pragma("unroll") for (int i = 0; i < 4; i++) { \
;       *(u32x4*)(dA + (lr + i * 32) * 72 + lc * 8) = RA[i]; \
;       if (i < 2 * NI) *(u32x4*)(dW + (lr + i * 32) * 72 + lc * 8) = RW[i]; } }
; template <int NI>
; DI void gemm_core(f32x16 (&acc)[2][NI], const u16* __restrict__ A, int lda, const u16* __restrict__ W, int ldw, int K,
;                   u16* sA0, u16* sW0) {
;     ...
;   const int nk = K >> 6;
;   G_LOAD(raA, rwA, 0)
;   G_STORE(raA, rwA, 0)
;   G_LOAD(raA, rwA, 1)
;   if (nk > 2) G_LOAD(raB, rwB, 2)
;   __syncthreads();
;   for (int kt = 0; kt < nk; kt += 2) {
;     G_STORE(raA, rwA, 1)
;     if (kt + 3 < nk) G_LOAD(raA, rwA, kt + 3)
;     G_COMPUTE(0)
;     __syncthreads();
;     if (kt + 2 < nk) G_STORE(raB, rwB, 0)
;     if (kt + 4 < nk) G_LOAD(raB, rwB, kt + 4)
;     G_COMPUTE(1)
;     __syncthreads();
	s_waitcnt vmcnt(15)
	ds_write_b128 v89, v[112:115] offset:36864
	s_waitcnt vmcnt(14)
	ds_write_b128 v89, v[116:119] offset:55296
	s_waitcnt vmcnt(13)
	ds_write_b128 v89, v[132:135] offset:41472
	s_waitcnt vmcnt(12)
	ds_write_b128 v89, v[152:155] offset:59904
	s_waitcnt vmcnt(11)
	ds_write_b128 v89, v[124:127] offset:46080
	s_waitcnt vmcnt(10)
	ds_write_b128 v89, v[156:159] offset:64512
	s_waitcnt vmcnt(9)
	ds_write_b128 v89, v[128:131] offset:50688
	s_waitcnt vmcnt(8)
	ds_write_b128 v90, v[160:163] offset:13824
	v_mfma_f32_32x32x16_bf16 v[16:31], v[136:139], v[120:123], v[16:31]
	ds_read_b128 v[112:115], v82
	ds_read_b128 v[116:119], v81 offset:18432
	ds_read_b128 v[120:123], v82 offset:32
	ds_read_b128 v[124:127], v81 offset:18464
	ds_read_b128 v[128:131], v81 offset:23040
	ds_read_b128 v[132:135], v81 offset:23072
	s_waitcnt lgkmcnt(4)
	v_mfma_f32_32x32x16_bf16 v[32:47], v[112:115], v[116:119], v[32:47]
	s_waitcnt lgkmcnt(1)
	v_mfma_f32_32x32x16_bf16 v[48:63], v[112:115], v[128:131], v[48:63]
	ds_read_b128 v[112:115], v82 offset:4608
	ds_read_b128 v[136:139], v82 offset:4640
	s_waitcnt lgkmcnt(1)
	v_mfma_f32_32x32x16_bf16 v[0:15], v[112:115], v[116:119], v[0:15]
	v_mfma_f32_32x32x16_bf16 v[16:31], v[112:115], v[128:131], v[16:31]
	v_mfma_f32_32x32x16_bf16 v[32:47], v[120:123], v[124:127], v[32:47]
	v_mfma_f32_32x32x16_bf16 v[48:63], v[120:123], v[132:135], v[48:63]
	s_waitcnt lgkmcnt(0)
	v_mfma_f32_32x32x16_bf16 v[0:15], v[136:139], v[124:127], v[0:15]
	ds_read_b128 v[112:115], v82 offset:64
	ds_read_b128 v[116:119], v81 offset:18496
	ds_read_b128 v[120:123], v82 offset:96
	ds_read_b128 v[124:127], v81 offset:18528
	v_mfma_f32_32x32x16_bf16 v[16:31], v[136:139], v[132:135], v[16:31]
	ds_read_b128 v[128:131], v81 offset:23104
	ds_read_b128 v[132:135], v81 offset:23136
	s_waitcnt lgkmcnt(4)
	v_mfma_f32_32x32x16_bf16 v[32:47], v[112:115], v[116:119], v[32:47]
	s_waitcnt lgkmcnt(1)
	v_mfma_f32_32x32x16_bf16 v[48:63], v[112:115], v[128:131], v[48:63]
	ds_read_b128 v[112:115], v82 offset:4672
	ds_read_b128 v[136:139], v82 offset:4704
	s_waitcnt lgkmcnt(1)
	v_mfma_f32_32x32x16_bf16 v[0:15], v[112:115], v[116:119], v[0:15]
	v_mfma_f32_32x32x16_bf16 v[16:31], v[112:115], v[128:131], v[16:31]
	v_add_u32_e32 v128, 0x81c0, v176
	v_mov_b32_e32 v129, v177
	global_load_dwordx4 v[112:115], v[86:87], off offset:896
	global_load_dwordx4 v[116:119], v[84:85], off offset:896
	v_lshlrev_b64 v[152:153], 1, v[128:129]
	v_lshl_add_u64 v[128:129], s[0:1], 0, v[152:153]
	global_load_dwordx4 v[128:131], v[128:129], off
	v_lshl_add_u64 v[152:153], s[36:37], 0, v[152:153]
	v_mfma_f32_32x32x16_bf16 v[32:47], v[120:123], v[124:127], v[32:47]
	global_load_dwordx4 v[152:155], v[152:153], off
	v_mfma_f32_32x32x16_bf16 v[48:63], v[120:123], v[132:135], v[48:63]
	v_add_u32_e32 v120, 0x101c0, v176
	v_mov_b32_e32 v121, v177
	v_lshlrev_b64 v[156:157], 1, v[120:121]
	v_lshl_add_u64 v[120:121], s[0:1], 0, v[156:157]
	global_load_dwordx4 v[120:123], v[120:121], off
	v_lshl_add_u64 v[156:157], s[36:37], 0, v[156:157]
	global_load_dwordx4 v[156:159], v[156:157], off
	s_waitcnt lgkmcnt(0)
	v_mfma_f32_32x32x16_bf16 v[0:15], v[136:139], v[124:127], v[0:15]
	v_add_u32_e32 v124, 0x181c0, v176
	v_mov_b32_e32 v125, v177
	v_lshlrev_b64 v[160:161], 1, v[124:125]
	v_lshl_add_u64 v[124:125], s[0:1], 0, v[160:161]
	global_load_dwordx4 v[124:127], v[124:125], off
	v_lshl_add_u64 v[160:161], s[36:37], 0, v[160:161]
	global_load_dwordx4 v[160:163], v[160:161], off
	s_barrier
	s_waitcnt vmcnt(15)
	ds_write_b128 v89, v[92:95]
	s_waitcnt vmcnt(14)
	ds_write_b128 v89, v[96:99] offset:18432
	s_waitcnt vmcnt(13)
	ds_write_b128 v89, v[108:111] offset:4608
	s_waitcnt vmcnt(12)
	ds_write_b128 v89, v[140:143] offset:23040
	s_waitcnt vmcnt(11)
	ds_write_b128 v89, v[100:103] offset:9216
	s_waitcnt vmcnt(10)
	ds_write_b128 v89, v[144:147] offset:27648
	s_waitcnt vmcnt(9)
	ds_write_b128 v89, v[104:107] offset:13824
	s_waitcnt vmcnt(8)
	ds_write_b128 v89, v[148:151] offset:32256
	v_mfma_f32_32x32x16_bf16 v[16:31], v[136:139], v[132:135], v[16:31]
	ds_read_b128 v[92:95], v82 offset:36864
	ds_read_b128 v[96:99], v81 offset:55296
	ds_read_b128 v[100:103], v82 offset:36896
	ds_read_b128 v[104:107], v81 offset:55328
	ds_read_b128 v[108:111], v81 offset:59904
	ds_read_b128 v[132:135], v81 offset:59936
	s_waitcnt lgkmcnt(4)
	v_mfma_f32_32x32x16_bf16 v[32:47], v[92:95], v[96:99], v[32:47]
	s_waitcnt lgkmcnt(1)
	v_mfma_f32_32x32x16_bf16 v[48:63], v[92:95], v[108:111], v[48:63]
	ds_read_b128 v[92:95], v82 offset:41472
	ds_read_b128 v[136:139], v82 offset:41504
	s_waitcnt lgkmcnt(1)
	v_mfma_f32_32x32x16_bf16 v[0:15], v[92:95], v[96:99], v[0:15]
	v_mfma_f32_32x32x16_bf16 v[16:31], v[92:95], v[108:111], v[16:31]
	v_mfma_f32_32x32x16_bf16 v[32:47], v[100:103], v[104:107], v[32:47]
	v_mfma_f32_32x32x16_bf16 v[48:63], v[100:103], v[132:135], v[48:63]
	s_waitcnt lgkmcnt(0)
	v_mfma_f32_32x32x16_bf16 v[0:15], v[136:139], v[104:107], v[0:15]
	ds_read_b128 v[92:95], v82 offset:36928
	ds_read_b128 v[96:99], v81 offset:55360
	ds_read_b128 v[100:103], v82 offset:36960
	ds_read_b128 v[104:107], v81 offset:55392
	v_mfma_f32_32x32x16_bf16 v[16:31], v[136:139], v[132:135], v[16:31]
	ds_read_b128 v[108:111], v81 offset:59968
	ds_read_b128 v[132:135], v81 offset:60000
	s_waitcnt lgkmcnt(4)
	v_mfma_f32_32x32x16_bf16 v[32:47], v[92:95], v[96:99], v[32:47]
	s_waitcnt lgkmcnt(1)
	v_mfma_f32_32x32x16_bf16 v[48:63], v[92:95], v[108:111], v[48:63]
	ds_read_b128 v[92:95], v82 offset:41536
	ds_read_b128 v[136:139], v82 offset:41568
	s_waitcnt lgkmcnt(1)
	v_mfma_f32_32x32x16_bf16 v[0:15], v[92:95], v[96:99], v[0:15]
	v_mfma_f32_32x32x16_bf16 v[16:31], v[92:95], v[108:111], v[16:31]
	v_add_u32_e32 v108, 0x8200, v176
	v_mov_b32_e32 v109, v177
	global_load_dwordx4 v[92:95], v[86:87], off offset:1024
	global_load_dwordx4 v[96:99], v[84:85], off offset:1024
	v_lshlrev_b64 v[140:141], 1, v[108:109]
	v_lshl_add_u64 v[108:109], s[0:1], 0, v[140:141]
	global_load_dwordx4 v[108:111], v[108:109], off
	v_lshl_add_u64 v[140:141], s[36:37], 0, v[140:141]
	v_mfma_f32_32x32x16_bf16 v[32:47], v[100:103], v[104:107], v[32:47]
	global_load_dwordx4 v[140:143], v[140:141], off
	v_mfma_f32_32x32x16_bf16 v[48:63], v[100:103], v[132:135], v[48:63]
	v_add_u32_e32 v100, 0x10200, v176
	v_mov_b32_e32 v101, v177
	v_lshlrev_b64 v[144:145], 1, v[100:101]
	v_lshl_add_u64 v[100:101], s[0:1], 0, v[144:145]
	global_load_dwordx4 v[100:103], v[100:101], off
	v_lshl_add_u64 v[144:145], s[36:37], 0, v[144:145]
	global_load_dwordx4 v[144:147], v[144:145], off
	s_waitcnt lgkmcnt(0)
	v_mfma_f32_32x32x16_bf16 v[0:15], v[136:139], v[104:107], v[0:15]
	v_add_u32_e32 v104, 0x18200, v176
	v_mov_b32_e32 v105, v177
	v_lshlrev_b64 v[148:149], 1, v[104:105]
	v_lshl_add_u64 v[104:105], s[0:1], 0, v[148:149]
	v_lshl_add_u64 v[148:149], s[36:37], 0, v[148:149]
	global_load_dwordx4 v[104:107], v[104:105], off
	s_nop 0
	global_load_dwordx4 v[148:151], v[148:149], off
	s_barrier
; #define G_LOAD(RA, RW, kt_) { _Pragma("unroll") for (int i = 0; i < 4; i++) { \
;       RA[i] = *(const u32x4*)(A + (aoff + (unsigned)(i * 32 * lda) + (unsigned)((kt_) * 64))); \
;       if (i < 2 * NI) RW[i] = *(const u32x4*)(W + (woff + (unsigned)(i * 32 * ldw) + (unsigned)((kt_) * 64))); } }
; #define G_STORE(RA, RW, buf_) { u16* dA = sA0 + (buf_) * GBUF; u16* dW = sW0 + (buf_) * GBUF; _Pragma("unroll") for (int i = 0; i < 4; i++) { \
;       *(u32x4*)(dA + (lr + i * 32) * 72 + lc * 8) = RA[i]; \
;       if (i < 2 * NI) *(u32x4*)(dW + (lr + i * 32) * 72 + lc * 8) = RW[i]; } }
; template <int NI>
; DI void gemm_core(f32x16 (&acc)[2][NI], const u16* __restrict__ A, int lda, const u16* __restrict__ W, int ldw, int K,
;                   u16* sA0, u16* sW0) {
;     ...
;   const int nk = K >> 6;
;   G_LOAD(raA, rwA, 0)
;   G_STORE(raA, rwA, 0)
;   G_LOAD(raA, rwA, 1)
;   if (nk > 2) G_LOAD(raB, rwB, 2)
;   __syncthreads();
;   for (int kt = 0; kt < nk; kt += 2) {
;     G_STORE(raA, rwA, 1)
;     if (kt + 3 < nk) G_LOAD(raA, rwA, kt + 3)
;     G_COMPUTE(0)
;     __syncthreads();
;     if (kt + 2 < nk) G_STORE(raB, rwB, 0)
;     if (kt + 4 < nk) G_LOAD(raB, rwB, kt + 4)
;     G_COMPUTE(1)
;     __syncthreads();
	s_waitcnt vmcnt(15)
	ds_write_b128 v89, v[112:115] offset:36864
	s_waitcnt vmcnt(14)
	ds_write_b128 v89, v[116:119] offset:55296
	s_waitcnt vmcnt(13)
	ds_write_b128 v89, v[128:131] offset:41472
	s_waitcnt vmcnt(12)
	ds_write_b128 v89, v[152:155] offset:59904
	s_waitcnt vmcnt(11)
	ds_write_b128 v89, v[120:123] offset:46080
	s_waitcnt vmcnt(10)
	ds_write_b128 v89, v[156:159] offset:64512
	s_waitcnt vmcnt(9)
	ds_write_b128 v89, v[124:127] offset:50688
	s_waitcnt vmcnt(8)
	ds_write_b128 v90, v[160:163] offset:13824
	v_mfma_f32_32x32x16_bf16 v[16:31], v[136:139], v[132:135], v[16:31]
	ds_read_b128 v[112:115], v82
	ds_read_b128 v[116:119], v81 offset:18432
	ds_read_b128 v[120:123], v82 offset:32
	ds_read_b128 v[124:127], v81 offset:18464
	ds_read_b128 v[128:131], v81 offset:23040
	ds_read_b128 v[132:135], v81 offset:23072
	s_waitcnt lgkmcnt(4)
	v_mfma_f32_32x32x16_bf16 v[32:47], v[112:115], v[116:119], v[32:47]
	s_waitcnt lgkmcnt(1)
	v_mfma_f32_32x32x16_bf16 v[48:63], v[112:115], v[128:131], v[48:63]
	ds_read_b128 v[112:115], v82 offset:4608
	ds_read_b128 v[136:139], v82 offset:4640
	s_waitcnt lgkmcnt(1)
	v_mfma_f32_32x32x16_bf16 v[0:15], v[112:115], v[116:119], v[0:15]
	v_mfma_f32_32x32x16_bf16 v[16:31], v[112:115], v[128:131], v[16:31]
	v_mfma_f32_32x32x16_bf16 v[32:47], v[120:123], v[124:127], v[32:47]
	v_mfma_f32_32x32x16_bf16 v[48:63], v[120:123], v[132:135], v[48:63]
	s_waitcnt lgkmcnt(0)
	v_mfma_f32_32x32x16_bf16 v[0:15], v[136:139], v[124:127], v[0:15]
	ds_read_b128 v[112:115], v82 offset:64
	ds_read_b128 v[116:119], v81 offset:18496
	ds_read_b128 v[120:123], v82 offset:96
	ds_read_b128 v[124:127], v81 offset:18528
	v_mfma_f32_32x32x16_bf16 v[16:31], v[136:139], v[132:135], v[16:31]
	ds_read_b128 v[128:131], v81 offset:23104
	ds_read_b128 v[132:135], v81 offset:23136
	s_waitcnt lgkmcnt(4)
	v_mfma_f32_32x32x16_bf16 v[32:47], v[112:115], v[116:119], v[32:47]
	s_waitcnt lgkmcnt(1)
	v_mfma_f32_32x32x16_bf16 v[48:63], v[112:115], v[128:131], v[48:63]
	ds_read_b128 v[112:115], v82 offset:4672
	ds_read_b128 v[136:139], v82 offset:4704
	s_waitcnt lgkmcnt(1)
	v_mfma_f32_32x32x16_bf16 v[0:15], v[112:115], v[116:119], v[0:15]
	v_mfma_f32_32x32x16_bf16 v[16:31], v[112:115], v[128:131], v[16:31]
	v_add_u32_e32 v128, 0x8240, v176
	v_mov_b32_e32 v129, v177
	global_load_dwordx4 v[112:115], v[86:87], off offset:1152
	global_load_dwordx4 v[116:119], v[84:85], off offset:1152
	v_lshlrev_b64 v[152:153], 1, v[128:129]
	v_lshl_add_u64 v[128:129], s[0:1], 0, v[152:153]
	global_load_dwordx4 v[128:131], v[128:129], off
	v_lshl_add_u64 v[152:153], s[36:37], 0, v[152:153]
	v_mfma_f32_32x32x16_bf16 v[32:47], v[120:123], v[124:127], v[32:47]
	global_load_dwordx4 v[152:155], v[152:153], off
	v_mfma_f32_32x32x16_bf16 v[48:63], v[120:123], v[132:135], v[48:63]
	v_add_u32_e32 v120, 0x10240, v176
	v_mov_b32_e32 v121, v177
	v_lshlrev_b64 v[156:157], 1, v[120:121]
	v_lshl_add_u64 v[120:121], s[0:1], 0, v[156:157]
	global_load_dwordx4 v[120:123], v[120:121], off
	v_lshl_add_u64 v[156:157], s[36:37], 0, v[156:157]
	global_load_dwordx4 v[156:159], v[156:157], off
	s_waitcnt lgkmcnt(0)
	v_mfma_f32_32x32x16_bf16 v[0:15], v[136:139], v[124:127], v[0:15]
	v_add_u32_e32 v124, 0x18240, v176
	v_mov_b32_e32 v125, v177
	v_lshlrev_b64 v[160:161], 1, v[124:125]
	v_lshl_add_u64 v[124:125], s[0:1], 0, v[160:161]
	global_load_dwordx4 v[124:127], v[124:125], off
	v_lshl_add_u64 v[160:161], s[36:37], 0, v[160:161]
	global_load_dwordx4 v[160:163], v[160:161], off
	s_barrier
	s_waitcnt vmcnt(15)
	ds_write_b128 v89, v[92:95]
	s_waitcnt vmcnt(14)
	ds_write_b128 v89, v[96:99] offset:18432
	s_waitcnt vmcnt(13)
	ds_write_b128 v89, v[108:111] offset:4608
	s_waitcnt vmcnt(12)
	ds_write_b128 v89, v[140:143] offset:23040
	s_waitcnt vmcnt(11)
	ds_write_b128 v89, v[100:103] offset:9216
	s_waitcnt vmcnt(10)
	ds_write_b128 v89, v[144:147] offset:27648
	s_waitcnt vmcnt(9)
	ds_write_b128 v89, v[104:107] offset:13824
	s_waitcnt vmcnt(8)
	ds_write_b128 v89, v[148:151] offset:32256
	v_mfma_f32_32x32x16_bf16 v[16:31], v[136:139], v[132:135], v[16:31]
	ds_read_b128 v[92:95], v82 offset:36864
	ds_read_b128 v[96:99], v81 offset:55296
	ds_read_b128 v[100:103], v82 offset:36896
	ds_read_b128 v[104:107], v81 offset:55328
	ds_read_b128 v[108:111], v81 offset:59904
	ds_read_b128 v[132:135], v81 offset:59936
	s_waitcnt lgkmcnt(4)
	v_mfma_f32_32x32x16_bf16 v[32:47], v[92:95], v[96:99], v[32:47]
	s_waitcnt lgkmcnt(1)
	v_mfma_f32_32x32x16_bf16 v[48:63], v[92:95], v[108:111], v[48:63]
	ds_read_b128 v[92:95], v82 offset:41472
	ds_read_b128 v[136:139], v82 offset:41504
	s_waitcnt lgkmcnt(1)
	v_mfma_f32_32x32x16_bf16 v[0:15], v[92:95], v[96:99], v[0:15]
	v_mfma_f32_32x32x16_bf16 v[16:31], v[92:95], v[108:111], v[16:31]
	v_mfma_f32_32x32x16_bf16 v[32:47], v[100:103], v[104:107], v[32:47]
	v_mfma_f32_32x32x16_bf16 v[48:63], v[100:103], v[132:135], v[48:63]
	s_waitcnt lgkmcnt(0)
	v_mfma_f32_32x32x16_bf16 v[0:15], v[136:139], v[104:107], v[0:15]
	ds_read_b128 v[92:95], v82 offset:36928
	ds_read_b128 v[96:99], v81 offset:55360
	ds_read_b128 v[100:103], v82 offset:36960
	ds_read_b128 v[104:107], v81 offset:55392
	v_mfma_f32_32x32x16_bf16 v[16:31], v[136:139], v[132:135], v[16:31]
	ds_read_b128 v[108:111], v81 offset:59968
	ds_read_b128 v[132:135], v81 offset:60000
	s_waitcnt lgkmcnt(4)
	v_mfma_f32_32x32x16_bf16 v[32:47], v[92:95], v[96:99], v[32:47]
	s_waitcnt lgkmcnt(1)
	v_mfma_f32_32x32x16_bf16 v[48:63], v[92:95], v[108:111], v[48:63]
	ds_read_b128 v[92:95], v82 offset:41536
	ds_read_b128 v[136:139], v82 offset:41568
	s_waitcnt lgkmcnt(1)
	v_mfma_f32_32x32x16_bf16 v[0:15], v[92:95], v[96:99], v[0:15]
	v_mfma_f32_32x32x16_bf16 v[16:31], v[92:95], v[108:111], v[16:31]
	v_add_u32_e32 v108, 0x8280, v176
	v_mov_b32_e32 v109, v177
	global_load_dwordx4 v[92:95], v[86:87], off offset:1280
	global_load_dwordx4 v[96:99], v[84:85], off offset:1280
	v_lshlrev_b64 v[140:141], 1, v[108:109]
	v_lshl_add_u64 v[108:109], s[0:1], 0, v[140:141]
	global_load_dwordx4 v[108:111], v[108:109], off
	v_lshl_add_u64 v[140:141], s[36:37], 0, v[140:141]
	v_mfma_f32_32x32x16_bf16 v[32:47], v[100:103], v[104:107], v[32:47]
	global_load_dwordx4 v[140:143], v[140:141], off
	v_mfma_f32_32x32x16_bf16 v[48:63], v[100:103], v[132:135], v[48:63]
	v_add_u32_e32 v100, 0x10280, v176
	v_mov_b32_e32 v101, v177
	v_lshlrev_b64 v[144:145], 1, v[100:101]
	v_lshl_add_u64 v[100:101], s[0:1], 0, v[144:145]
	global_load_dwordx4 v[100:103], v[100:101], off
	v_lshl_add_u64 v[144:145], s[36:37], 0, v[144:145]
	global_load_dwordx4 v[144:147], v[144:145], off
	s_waitcnt lgkmcnt(0)
	v_mfma_f32_32x32x16_bf16 v[0:15], v[136:139], v[104:107], v[0:15]
	v_add_u32_e32 v104, 0x18280, v176
	v_mov_b32_e32 v105, v177
	v_lshlrev_b64 v[148:149], 1, v[104:105]
	v_lshl_add_u64 v[104:105], s[0:1], 0, v[148:149]
	v_lshl_add_u64 v[148:149], s[36:37], 0, v[148:149]
	global_load_dwordx4 v[104:107], v[104:105], off
	s_nop 0
	global_load_dwordx4 v[148:151], v[148:149], off
	s_barrier
; #define G_LOAD(RA, RW, kt_) { _Pragma("unroll") for (int i = 0; i < 4; i++) { \
;       RA[i] = *(const u32x4*)(A + (aoff + (unsigned)(i * 32 * lda) + (unsigned)((kt_) * 64))); \
;       if (i < 2 * NI) RW[i] = *(const u32x4*)(W + (woff + (unsigned)(i * 32 * ldw) + (unsigned)((kt_) * 64))); } }
; #define G_STORE(RA, RW, buf_) { u16* dA = sA0 + (buf_) * GBUF; u16* dW = sW0 + (buf_) * GBUF; _Pragma("unroll") for (int i = 0; i < 4; i++) { \
;       *(u32x4*)(dA + (lr + i * 32) * 72 + lc * 8) = RA[i]; \
;       if (i < 2 * NI) *(u32x4*)(dW + (lr + i * 32) * 72 + lc * 8) = RW[i]; } }
; template <int NI>
; DI void gemm_core(f32x16 (&acc)[2][NI], const u16* __restrict__ A, int lda, const u16* __restrict__ W, int ldw, int K,
;                   u16* sA0, u16* sW0) {
;     ...
;   const int nk = K >> 6;
;   G_LOAD(raA, rwA, 0)
;   G_STORE(raA, rwA, 0)
;   G_LOAD(raA, rwA, 1)
;   if (nk > 2) G_LOAD(raB, rwB, 2)
;   __syncthreads();
;   for (int kt = 0; kt < nk; kt += 2) {
;     G_STORE(raA, rwA, 1)
;     if (kt + 3 < nk) G_LOAD(raA, rwA, kt + 3)
;     G_COMPUTE(0)
;     __syncthreads();
;     if (kt + 2 < nk) G_STORE(raB, rwB, 0)
;     if (kt + 4 < nk) G_LOAD(raB, rwB, kt + 4)
;     G_COMPUTE(1)
;     __syncthreads();
	s_waitcnt vmcnt(15)
	ds_write_b128 v89, v[112:115] offset:36864
	s_waitcnt vmcnt(14)
	ds_write_b128 v89, v[116:119] offset:55296
	s_waitcnt vmcnt(13)
	ds_write_b128 v89, v[128:131] offset:41472
	s_waitcnt vmcnt(12)
	ds_write_b128 v89, v[152:155] offset:59904
	s_waitcnt vmcnt(11)
	ds_write_b128 v89, v[120:123] offset:46080
	s_waitcnt vmcnt(10)
	ds_write_b128 v89, v[156:159] offset:64512
	s_waitcnt vmcnt(9)
	ds_write_b128 v89, v[124:127] offset:50688
	s_waitcnt vmcnt(8)
	ds_write_b128 v90, v[160:163] offset:13824
	v_mfma_f32_32x32x16_bf16 v[16:31], v[136:139], v[132:135], v[16:31]
	ds_read_b128 v[112:115], v82
	ds_read_b128 v[116:119], v81 offset:18432
	ds_read_b128 v[120:123], v82 offset:32
	ds_read_b128 v[124:127], v81 offset:18464
	ds_read_b128 v[128:131], v81 offset:23040
	ds_read_b128 v[132:135], v81 offset:23072
	s_waitcnt lgkmcnt(4)
	v_mfma_f32_32x32x16_bf16 v[32:47], v[112:115], v[116:119], v[32:47]
	s_waitcnt lgkmcnt(1)
	v_mfma_f32_32x32x16_bf16 v[48:63], v[112:115], v[128:131], v[48:63]
	ds_read_b128 v[112:115], v82 offset:4608
	ds_read_b128 v[136:139], v82 offset:4640
	s_waitcnt lgkmcnt(1)
	v_mfma_f32_32x32x16_bf16 v[0:15], v[112:115], v[116:119], v[0:15]
	v_mfma_f32_32x32x16_bf16 v[16:31], v[112:115], v[128:131], v[16:31]
	v_mfma_f32_32x32x16_bf16 v[32:47], v[120:123], v[124:127], v[32:47]
	v_mfma_f32_32x32x16_bf16 v[48:63], v[120:123], v[132:135], v[48:63]
	s_waitcnt lgkmcnt(0)
	v_mfma_f32_32x32x16_bf16 v[0:15], v[136:139], v[124:127], v[0:15]
	ds_read_b128 v[112:115], v82 offset:64
	ds_read_b128 v[116:119], v81 offset:18496
	ds_read_b128 v[120:123], v82 offset:96
	ds_read_b128 v[124:127], v81 offset:18528
	v_mfma_f32_32x32x16_bf16 v[16:31], v[136:139], v[132:135], v[16:31]
	ds_read_b128 v[128:131], v81 offset:23104
	ds_read_b128 v[132:135], v81 offset:23136
	s_waitcnt lgkmcnt(4)
	v_mfma_f32_32x32x16_bf16 v[32:47], v[112:115], v[116:119], v[32:47]
	s_waitcnt lgkmcnt(1)
	v_mfma_f32_32x32x16_bf16 v[48:63], v[112:115], v[128:131], v[48:63]
	ds_read_b128 v[112:115], v82 offset:4672
	ds_read_b128 v[136:139], v82 offset:4704
	s_waitcnt lgkmcnt(1)
	v_mfma_f32_32x32x16_bf16 v[0:15], v[112:115], v[116:119], v[0:15]
	v_mfma_f32_32x32x16_bf16 v[16:31], v[112:115], v[128:131], v[16:31]
	v_add_u32_e32 v128, 0x82c0, v176
	v_mov_b32_e32 v129, v177
	global_load_dwordx4 v[112:115], v[86:87], off offset:1408
	global_load_dwordx4 v[116:119], v[84:85], off offset:1408
	v_lshlrev_b64 v[152:153], 1, v[128:129]
	v_lshl_add_u64 v[128:129], s[0:1], 0, v[152:153]
	global_load_dwordx4 v[128:131], v[128:129], off
	v_lshl_add_u64 v[152:153], s[36:37], 0, v[152:153]
	v_mfma_f32_32x32x16_bf16 v[32:47], v[120:123], v[124:127], v[32:47]
	global_load_dwordx4 v[152:155], v[152:153], off
	v_mfma_f32_32x32x16_bf16 v[48:63], v[120:123], v[132:135], v[48:63]
	v_add_u32_e32 v120, 0x102c0, v176
	v_mov_b32_e32 v121, v177
	v_lshlrev_b64 v[156:157], 1, v[120:121]
	v_lshl_add_u64 v[120:121], s[0:1], 0, v[156:157]
	global_load_dwordx4 v[120:123], v[120:121], off
	v_lshl_add_u64 v[156:157], s[36:37], 0, v[156:157]
	global_load_dwordx4 v[156:159], v[156:157], off
	s_waitcnt lgkmcnt(0)
	v_mfma_f32_32x32x16_bf16 v[0:15], v[136:139], v[124:127], v[0:15]
	v_add_u32_e32 v124, 0x182c0, v176
	v_mov_b32_e32 v125, v177
	v_lshlrev_b64 v[160:161], 1, v[124:125]
	v_lshl_add_u64 v[124:125], s[0:1], 0, v[160:161]
	global_load_dwordx4 v[124:127], v[124:125], off
	v_lshl_add_u64 v[160:161], s[36:37], 0, v[160:161]
	global_load_dwordx4 v[160:163], v[160:161], off
	s_barrier
	s_waitcnt vmcnt(15)
	ds_write_b128 v89, v[92:95]
	s_waitcnt vmcnt(14)
	ds_write_b128 v89, v[96:99] offset:18432
	s_waitcnt vmcnt(13)
	ds_write_b128 v89, v[108:111] offset:4608
	s_waitcnt vmcnt(12)
	ds_write_b128 v89, v[140:143] offset:23040
	s_waitcnt vmcnt(11)
	ds_write_b128 v89, v[100:103] offset:9216
	s_waitcnt vmcnt(10)
	ds_write_b128 v89, v[144:147] offset:27648
	s_waitcnt vmcnt(9)
	ds_write_b128 v89, v[104:107] offset:13824
	s_waitcnt vmcnt(8)
	ds_write_b128 v89, v[148:151] offset:32256
	v_mfma_f32_32x32x16_bf16 v[16:31], v[136:139], v[132:135], v[16:31]
	ds_read_b128 v[92:95], v82 offset:36864
	ds_read_b128 v[96:99], v81 offset:55296
	ds_read_b128 v[100:103], v82 offset:36896
	ds_read_b128 v[104:107], v81 offset:55328
	ds_read_b128 v[108:111], v81 offset:59904
	ds_read_b128 v[132:135], v81 offset:59936
	s_waitcnt lgkmcnt(4)
	v_mfma_f32_32x32x16_bf16 v[32:47], v[92:95], v[96:99], v[32:47]
	s_waitcnt lgkmcnt(1)
	v_mfma_f32_32x32x16_bf16 v[48:63], v[92:95], v[108:111], v[48:63]
	ds_read_b128 v[92:95], v82 offset:41472
	ds_read_b128 v[136:139], v82 offset:41504
	s_waitcnt lgkmcnt(1)
	v_mfma_f32_32x32x16_bf16 v[0:15], v[92:95], v[96:99], v[0:15]
	v_mfma_f32_32x32x16_bf16 v[16:31], v[92:95], v[108:111], v[16:31]
	v_mfma_f32_32x32x16_bf16 v[32:47], v[100:103], v[104:107], v[32:47]
	v_mfma_f32_32x32x16_bf16 v[48:63], v[100:103], v[132:135], v[48:63]
	s_waitcnt lgkmcnt(0)
	v_mfma_f32_32x32x16_bf16 v[0:15], v[136:139], v[104:107], v[0:15]
	ds_read_b128 v[92:95], v82 offset:36928
	ds_read_b128 v[96:99], v81 offset:55360
	ds_read_b128 v[100:103], v82 offset:36960
	ds_read_b128 v[104:107], v81 offset:55392
	v_mfma_f32_32x32x16_bf16 v[16:31], v[136:139], v[132:135], v[16:31]
	ds_read_b128 v[108:111], v81 offset:59968
	ds_read_b128 v[132:135], v81 offset:60000
	s_waitcnt lgkmcnt(4)
	v_mfma_f32_32x32x16_bf16 v[32:47], v[92:95], v[96:99], v[32:47]
	s_waitcnt lgkmcnt(1)
	v_mfma_f32_32x32x16_bf16 v[48:63], v[92:95], v[108:111], v[48:63]
	ds_read_b128 v[92:95], v82 offset:41536
	ds_read_b128 v[136:139], v82 offset:41568
	s_waitcnt lgkmcnt(1)
	v_mfma_f32_32x32x16_bf16 v[0:15], v[92:95], v[96:99], v[0:15]
	v_mfma_f32_32x32x16_bf16 v[16:31], v[92:95], v[108:111], v[16:31]
	v_add_u32_e32 v108, 0x8300, v176
	v_mov_b32_e32 v109, v177
	global_load_dwordx4 v[92:95], v[86:87], off offset:1536
	global_load_dwordx4 v[96:99], v[84:85], off offset:1536
	v_lshlrev_b64 v[140:141], 1, v[108:109]
	v_lshl_add_u64 v[108:109], s[0:1], 0, v[140:141]
	global_load_dwordx4 v[108:111], v[108:109], off
	v_lshl_add_u64 v[140:141], s[36:37], 0, v[140:141]
	v_mfma_f32_32x32x16_bf16 v[32:47], v[100:103], v[104:107], v[32:47]
	global_load_dwordx4 v[140:143], v[140:141], off
	v_mfma_f32_32x32x16_bf16 v[48:63], v[100:103], v[132:135], v[48:63]
	v_add_u32_e32 v100, 0x10300, v176
	v_mov_b32_e32 v101, v177
	v_lshlrev_b64 v[144:145], 1, v[100:101]
	v_lshl_add_u64 v[100:101], s[0:1], 0, v[144:145]
	global_load_dwordx4 v[100:103], v[100:101], off
	v_lshl_add_u64 v[144:145], s[36:37], 0, v[144:145]
	global_load_dwordx4 v[144:147], v[144:145], off
	s_waitcnt lgkmcnt(0)
	v_mfma_f32_32x32x16_bf16 v[0:15], v[136:139], v[104:107], v[0:15]
	v_add_u32_e32 v104, 0x18300, v176
	v_mov_b32_e32 v105, v177
	v_lshlrev_b64 v[148:149], 1, v[104:105]
	v_lshl_add_u64 v[104:105], s[0:1], 0, v[148:149]
	v_lshl_add_u64 v[148:149], s[36:37], 0, v[148:149]
	global_load_dwordx4 v[104:107], v[104:105], off
	s_nop 0
	global_load_dwordx4 v[148:151], v[148:149], off
	s_barrier
; #define G_LOAD(RA, RW, kt_) { _Pragma("unroll") for (int i = 0; i < 4; i++) { \
;       RA[i] = *(const u32x4*)(A + (aoff + (unsigned)(i * 32 * lda) + (unsigned)((kt_) * 64))); \
;       if (i < 2 * NI) RW[i] = *(const u32x4*)(W + (woff + (unsigned)(i * 32 * ldw) + (unsigned)((kt_) * 64))); } }
; #define G_STORE(RA, RW, buf_) { u16* dA = sA0 + (buf_) * GBUF; u16* dW = sW0 + (buf_) * GBUF; _Pragma("unroll") for (int i = 0; i < 4; i++) { \
;       *(u32x4*)(dA + (lr + i * 32) * 72 + lc * 8) = RA[i]; \
;       if (i < 2 * NI) *(u32x4*)(dW + (lr + i * 32) * 72 + lc * 8) = RW[i]; } }
; template <int NI>
; DI void gemm_core(f32x16 (&acc)[2][NI], const u16* __restrict__ A, int lda, const u16* __restrict__ W, int ldw, int K,
;                   u16* sA0, u16* sW0) {
;     ...
;   const int nk = K >> 6;
;   G_LOAD(raA, rwA, 0)
;   G_STORE(raA, rwA, 0)
;   G_LOAD(raA, rwA, 1)
;   if (nk > 2) G_LOAD(raB, rwB, 2)
;   __syncthreads();
;   for (int kt = 0; kt < nk; kt += 2) {
;     G_STORE(raA, rwA, 1)
;     if (kt + 3 < nk) G_LOAD(raA, rwA, kt + 3)
;     G_COMPUTE(0)
;     __syncthreads();
;     if (kt + 2 < nk) G_STORE(raB, rwB, 0)
;     if (kt + 4 < nk) G_LOAD(raB, rwB, kt + 4)
;     G_COMPUTE(1)
;     __syncthreads();
	s_waitcnt vmcnt(15)
	ds_write_b128 v89, v[112:115] offset:36864
	s_waitcnt vmcnt(14)
	ds_write_b128 v89, v[116:119] offset:55296
	s_waitcnt vmcnt(13)
	ds_write_b128 v89, v[128:131] offset:41472
	s_waitcnt vmcnt(12)
	ds_write_b128 v89, v[152:155] offset:59904
	s_waitcnt vmcnt(11)
	ds_write_b128 v89, v[120:123] offset:46080
	s_waitcnt vmcnt(10)
	ds_write_b128 v89, v[156:159] offset:64512
	s_waitcnt vmcnt(9)
	ds_write_b128 v89, v[124:127] offset:50688
	s_waitcnt vmcnt(8)
	ds_write_b128 v90, v[160:163] offset:13824
	v_mfma_f32_32x32x16_bf16 v[16:31], v[136:139], v[132:135], v[16:31]
	ds_read_b128 v[112:115], v82
	ds_read_b128 v[116:119], v81 offset:18432
	ds_read_b128 v[120:123], v82 offset:32
	ds_read_b128 v[124:127], v81 offset:18464
	ds_read_b128 v[128:131], v81 offset:23040
	ds_read_b128 v[132:135], v81 offset:23072
	s_waitcnt lgkmcnt(4)
	v_mfma_f32_32x32x16_bf16 v[32:47], v[112:115], v[116:119], v[32:47]
	s_waitcnt lgkmcnt(1)
	v_mfma_f32_32x32x16_bf16 v[48:63], v[112:115], v[128:131], v[48:63]
	ds_read_b128 v[112:115], v82 offset:4608
	ds_read_b128 v[136:139], v82 offset:4640
	s_waitcnt lgkmcnt(1)
	v_mfma_f32_32x32x16_bf16 v[0:15], v[112:115], v[116:119], v[0:15]
	v_mfma_f32_32x32x16_bf16 v[16:31], v[112:115], v[128:131], v[16:31]
	v_mfma_f32_32x32x16_bf16 v[32:47], v[120:123], v[124:127], v[32:47]
	v_mfma_f32_32x32x16_bf16 v[48:63], v[120:123], v[132:135], v[48:63]
	s_waitcnt lgkmcnt(0)
	v_mfma_f32_32x32x16_bf16 v[0:15], v[136:139], v[124:127], v[0:15]
	ds_read_b128 v[112:115], v82 offset:64
	ds_read_b128 v[116:119], v81 offset:18496
	ds_read_b128 v[120:123], v82 offset:96
	ds_read_b128 v[124:127], v81 offset:18528
	v_mfma_f32_32x32x16_bf16 v[16:31], v[136:139], v[132:135], v[16:31]
	ds_read_b128 v[128:131], v81 offset:23104
	ds_read_b128 v[132:135], v81 offset:23136
	s_waitcnt lgkmcnt(4)
	v_mfma_f32_32x32x16_bf16 v[32:47], v[112:115], v[116:119], v[32:47]
	s_waitcnt lgkmcnt(1)
	v_mfma_f32_32x32x16_bf16 v[48:63], v[112:115], v[128:131], v[48:63]
	ds_read_b128 v[112:115], v82 offset:4672
	ds_read_b128 v[136:139], v82 offset:4704
	s_waitcnt lgkmcnt(1)
	v_mfma_f32_32x32x16_bf16 v[0:15], v[112:115], v[116:119], v[0:15]
	v_mfma_f32_32x32x16_bf16 v[16:31], v[112:115], v[128:131], v[16:31]
	v_add_u32_e32 v128, 0x8340, v176
	v_mov_b32_e32 v129, v177
	global_load_dwordx4 v[112:115], v[86:87], off offset:1664
	global_load_dwordx4 v[116:119], v[84:85], off offset:1664
	v_lshlrev_b64 v[152:153], 1, v[128:129]
	v_lshl_add_u64 v[128:129], s[0:1], 0, v[152:153]
	global_load_dwordx4 v[128:131], v[128:129], off
	v_lshl_add_u64 v[152:153], s[36:37], 0, v[152:153]
	v_mfma_f32_32x32x16_bf16 v[32:47], v[120:123], v[124:127], v[32:47]
	global_load_dwordx4 v[152:155], v[152:153], off
	v_mfma_f32_32x32x16_bf16 v[48:63], v[120:123], v[132:135], v[48:63]
	v_add_u32_e32 v120, 0x10340, v176
	v_mov_b32_e32 v121, v177
	v_lshlrev_b64 v[156:157], 1, v[120:121]
	v_lshl_add_u64 v[120:121], s[0:1], 0, v[156:157]
	global_load_dwordx4 v[120:123], v[120:121], off
	v_lshl_add_u64 v[156:157], s[36:37], 0, v[156:157]
	global_load_dwordx4 v[156:159], v[156:157], off
	s_waitcnt lgkmcnt(0)
	v_mfma_f32_32x32x16_bf16 v[0:15], v[136:139], v[124:127], v[0:15]
	v_add_u32_e32 v124, 0x18340, v176
	v_mov_b32_e32 v125, v177
	v_lshlrev_b64 v[160:161], 1, v[124:125]
	v_lshl_add_u64 v[124:125], s[0:1], 0, v[160:161]
	global_load_dwordx4 v[124:127], v[124:125], off
	v_lshl_add_u64 v[160:161], s[36:37], 0, v[160:161]
	global_load_dwordx4 v[160:163], v[160:161], off
	s_barrier
	s_waitcnt vmcnt(15)
	ds_write_b128 v89, v[92:95]
	s_waitcnt vmcnt(14)
	ds_write_b128 v89, v[96:99] offset:18432
	s_waitcnt vmcnt(13)
	ds_write_b128 v89, v[108:111] offset:4608
	s_waitcnt vmcnt(12)
	ds_write_b128 v89, v[140:143] offset:23040
	s_waitcnt vmcnt(11)
	ds_write_b128 v89, v[100:103] offset:9216
	s_waitcnt vmcnt(10)
	ds_write_b128 v89, v[144:147] offset:27648
	s_waitcnt vmcnt(9)
	ds_write_b128 v89, v[104:107] offset:13824
	s_waitcnt vmcnt(8)
	ds_write_b128 v89, v[148:151] offset:32256
	v_mfma_f32_32x32x16_bf16 v[16:31], v[136:139], v[132:135], v[16:31]
	ds_read_b128 v[92:95], v82 offset:36864
	ds_read_b128 v[96:99], v81 offset:55296
	ds_read_b128 v[100:103], v82 offset:36896
	ds_read_b128 v[104:107], v81 offset:55328
	ds_read_b128 v[108:111], v81 offset:59904
	ds_read_b128 v[132:135], v81 offset:59936
	s_waitcnt lgkmcnt(4)
	v_mfma_f32_32x32x16_bf16 v[32:47], v[92:95], v[96:99], v[32:47]
	s_waitcnt lgkmcnt(1)
	v_mfma_f32_32x32x16_bf16 v[48:63], v[92:95], v[108:111], v[48:63]
	ds_read_b128 v[92:95], v82 offset:41472
	ds_read_b128 v[136:139], v82 offset:41504
	s_waitcnt lgkmcnt(1)
	v_mfma_f32_32x32x16_bf16 v[0:15], v[92:95], v[96:99], v[0:15]
	v_mfma_f32_32x32x16_bf16 v[16:31], v[92:95], v[108:111], v[16:31]
	v_mfma_f32_32x32x16_bf16 v[32:47], v[100:103], v[104:107], v[32:47]
	v_mfma_f32_32x32x16_bf16 v[48:63], v[100:103], v[132:135], v[48:63]
	s_waitcnt lgkmcnt(0)
	v_mfma_f32_32x32x16_bf16 v[0:15], v[136:139], v[104:107], v[0:15]
	ds_read_b128 v[92:95], v82 offset:36928
	ds_read_b128 v[96:99], v81 offset:55360
	ds_read_b128 v[100:103], v82 offset:36960
	ds_read_b128 v[104:107], v81 offset:55392
	v_mfma_f32_32x32x16_bf16 v[16:31], v[136:139], v[132:135], v[16:31]
	ds_read_b128 v[108:111], v81 offset:59968
	ds_read_b128 v[132:135], v81 offset:60000
	s_waitcnt lgkmcnt(4)
	v_mfma_f32_32x32x16_bf16 v[32:47], v[92:95], v[96:99], v[32:47]
	s_waitcnt lgkmcnt(1)
	v_mfma_f32_32x32x16_bf16 v[48:63], v[92:95], v[108:111], v[48:63]
	ds_read_b128 v[92:95], v82 offset:41536
	ds_read_b128 v[136:139], v82 offset:41568
	s_waitcnt lgkmcnt(1)
	v_mfma_f32_32x32x16_bf16 v[0:15], v[92:95], v[96:99], v[0:15]
	v_mfma_f32_32x32x16_bf16 v[16:31], v[92:95], v[108:111], v[16:31]
	v_add_u32_e32 v108, 0x8380, v176
	v_mov_b32_e32 v109, v177
	global_load_dwordx4 v[92:95], v[86:87], off offset:1792
	global_load_dwordx4 v[96:99], v[84:85], off offset:1792
	v_lshlrev_b64 v[140:141], 1, v[108:109]
	v_lshl_add_u64 v[108:109], s[0:1], 0, v[140:141]
	global_load_dwordx4 v[108:111], v[108:109], off
	v_lshl_add_u64 v[140:141], s[36:37], 0, v[140:141]
	v_mfma_f32_32x32x16_bf16 v[32:47], v[100:103], v[104:107], v[32:47]
	global_load_dwordx4 v[140:143], v[140:141], off
	v_mfma_f32_32x32x16_bf16 v[48:63], v[100:103], v[132:135], v[48:63]
	v_add_u32_e32 v100, 0x10380, v176
	v_mov_b32_e32 v101, v177
	v_lshlrev_b64 v[144:145], 1, v[100:101]
	v_lshl_add_u64 v[100:101], s[0:1], 0, v[144:145]
	v_lshl_add_u64 v[144:145], s[36:37], 0, v[144:145]
	global_load_dwordx4 v[100:103], v[100:101], off
	s_waitcnt lgkmcnt(0)
	v_mfma_f32_32x32x16_bf16 v[0:15], v[136:139], v[104:107], v[0:15]
	v_add_u32_e32 v104, 0x18380, v176
	v_mov_b32_e32 v105, v177
	v_lshlrev_b64 v[148:149], 1, v[104:105]
	v_lshl_add_u64 v[104:105], s[0:1], 0, v[148:149]
	v_lshl_add_u64 v[148:149], s[36:37], 0, v[148:149]
	global_load_dwordx4 v[144:147], v[144:145], off
	s_nop 0
	global_load_dwordx4 v[104:107], v[104:105], off
	v_mfma_f32_32x32x16_bf16 v[16:31], v[136:139], v[132:135], v[16:31]
	global_load_dwordx4 v[148:151], v[148:149], off
	s_barrier
; #define G_LOAD(RA, RW, kt_) { _Pragma("unroll") for (int i = 0; i < 4; i++) { \
;       RA[i] = *(const u32x4*)(A + (aoff + (unsigned)(i * 32 * lda) + (unsigned)((kt_) * 64))); \
;       if (i < 2 * NI) RW[i] = *(const u32x4*)(W + (woff + (unsigned)(i * 32 * ldw) + (unsigned)((kt_) * 64))); } }
; #define G_STORE(RA, RW, buf_) { u16* dA = sA0 + (buf_) * GBUF; u16* dW = sW0 + (buf_) * GBUF; _Pragma("unroll") for (int i = 0; i < 4; i++) { \
;       *(u32x4*)(dA + (lr + i * 32) * 72 + lc * 8) = RA[i]; \
;       if (i < 2 * NI) *(u32x4*)(dW + (lr + i * 32) * 72 + lc * 8) = RW[i]; } }
; template <int NI>
; DI void gemm_core(f32x16 (&acc)[2][NI], const u16* __restrict__ A, int lda, const u16* __restrict__ W, int ldw, int K,
;                   u16* sA0, u16* sW0) {
;     ...
;   const int nk = K >> 6;
;   G_LOAD(raA, rwA, 0)
;   G_STORE(raA, rwA, 0)
;   G_LOAD(raA, rwA, 1)
;   if (nk > 2) G_LOAD(raB, rwB, 2)
;   __syncthreads();
;   for (int kt = 0; kt < nk; kt += 2) {
;     G_STORE(raA, rwA, 1)
;     if (kt + 3 < nk) G_LOAD(raA, rwA, kt + 3)
;     G_COMPUTE(0)
;     __syncthreads();
;     if (kt + 2 < nk) G_STORE(raB, rwB, 0)
;     if (kt + 4 < nk) G_LOAD(raB, rwB, kt + 4)
;     G_COMPUTE(1)
;     __syncthreads();
	s_waitcnt vmcnt(15)
	ds_write_b128 v89, v[112:115] offset:36864
	s_waitcnt vmcnt(14)
	ds_write_b128 v89, v[116:119] offset:55296
	s_waitcnt vmcnt(13)
	ds_write_b128 v89, v[128:131] offset:41472
	s_waitcnt vmcnt(12)
	ds_write_b128 v89, v[152:155] offset:59904
	s_waitcnt vmcnt(11)
	ds_write_b128 v89, v[120:123] offset:46080
	s_waitcnt vmcnt(10)
	ds_write_b128 v89, v[156:159] offset:64512
	s_waitcnt vmcnt(9)
	ds_write_b128 v89, v[124:127] offset:50688
	s_waitcnt vmcnt(8)
	ds_write_b128 v90, v[160:163] offset:13824
	ds_read_b128 v[112:115], v82
	ds_read_b128 v[116:119], v81 offset:18432
	ds_read_b128 v[120:123], v82 offset:32
	ds_read_b128 v[124:127], v81 offset:18464
	ds_read_b128 v[128:131], v81 offset:23040
	ds_read_b128 v[132:135], v81 offset:23072
	s_waitcnt lgkmcnt(4)
	v_mfma_f32_32x32x16_bf16 v[32:47], v[112:115], v[116:119], v[32:47]
	s_waitcnt lgkmcnt(1)
	v_mfma_f32_32x32x16_bf16 v[48:63], v[112:115], v[128:131], v[48:63]
	ds_read_b128 v[112:115], v82 offset:4608
	ds_read_b128 v[136:139], v82 offset:4640
	s_waitcnt lgkmcnt(1)
	v_mfma_f32_32x32x16_bf16 v[0:15], v[112:115], v[116:119], v[0:15]
	v_mfma_f32_32x32x16_bf16 v[16:31], v[112:115], v[128:131], v[16:31]
	v_mfma_f32_32x32x16_bf16 v[32:47], v[120:123], v[124:127], v[32:47]
	v_mfma_f32_32x32x16_bf16 v[48:63], v[120:123], v[132:135], v[48:63]
	s_waitcnt lgkmcnt(0)
	v_mfma_f32_32x32x16_bf16 v[0:15], v[136:139], v[124:127], v[0:15]
	ds_read_b128 v[112:115], v82 offset:64
	ds_read_b128 v[116:119], v81 offset:18496
	ds_read_b128 v[120:123], v82 offset:96
	ds_read_b128 v[124:127], v81 offset:18528
	v_mfma_f32_32x32x16_bf16 v[16:31], v[136:139], v[132:135], v[16:31]
	ds_read_b128 v[128:131], v81 offset:23104
	ds_read_b128 v[132:135], v81 offset:23136
	s_waitcnt lgkmcnt(4)
	v_mfma_f32_32x32x16_bf16 v[32:47], v[112:115], v[116:119], v[32:47]
	s_waitcnt lgkmcnt(1)
	v_mfma_f32_32x32x16_bf16 v[48:63], v[112:115], v[128:131], v[48:63]
	ds_read_b128 v[112:115], v82 offset:4672
	ds_read_b128 v[136:139], v82 offset:4704
	s_waitcnt lgkmcnt(1)
	v_mfma_f32_32x32x16_bf16 v[0:15], v[112:115], v[116:119], v[0:15]
	v_add_u32_e32 v116, 0x83c0, v176
	v_mov_b32_e32 v117, v177
	v_mfma_f32_32x32x16_bf16 v[16:31], v[112:115], v[128:131], v[16:31]
	v_lshlrev_b64 v[128:129], 1, v[116:117]
	global_load_dwordx4 v[112:115], v[86:87], off offset:1920
	v_lshl_add_u64 v[116:117], s[0:1], 0, v[128:129]
	v_lshl_add_u64 v[128:129], s[36:37], 0, v[128:129]
	global_load_dwordx4 v[116:119], v[116:117], off
	s_nop 0
	global_load_dwordx4 v[84:87], v[84:85], off offset:1920
	v_mfma_f32_32x32x16_bf16 v[32:47], v[120:123], v[124:127], v[32:47]
	v_mfma_f32_32x32x16_bf16 v[48:63], v[120:123], v[132:135], v[48:63]
	global_load_dwordx4 v[120:123], v[128:129], off
	v_add_u32_e32 v128, 0x103c0, v176
	v_mov_b32_e32 v129, v177
	v_lshlrev_b64 v[152:153], 1, v[128:129]
	v_lshl_add_u64 v[128:129], s[0:1], 0, v[152:153]
	v_add_u32_e32 v176, 0x183c0, v176
	global_load_dwordx4 v[128:131], v[128:129], off
	v_lshl_add_u64 v[152:153], s[36:37], 0, v[152:153]
	v_lshlrev_b64 v[156:157], 1, v[176:177]
	s_waitcnt lgkmcnt(0)
	v_mfma_f32_32x32x16_bf16 v[0:15], v[136:139], v[124:127], v[0:15]
	global_load_dwordx4 v[124:127], v[152:153], off
	v_lshl_add_u64 v[152:153], s[0:1], 0, v[156:157]
	global_load_dwordx4 v[152:155], v[152:153], off
	v_lshl_add_u64 v[156:157], s[36:37], 0, v[156:157]
	global_load_dwordx4 v[156:159], v[156:157], off
	s_barrier
	s_waitcnt vmcnt(15)
	ds_write_b128 v89, v[92:95]
	s_waitcnt vmcnt(14)
	ds_write_b128 v89, v[96:99] offset:18432
	s_waitcnt vmcnt(13)
	ds_write_b128 v89, v[108:111] offset:4608
	s_waitcnt vmcnt(12)
	ds_write_b128 v89, v[140:143] offset:23040
	s_waitcnt vmcnt(11)
	ds_write_b128 v89, v[100:103] offset:9216
	s_waitcnt vmcnt(10)
	ds_write_b128 v89, v[144:147] offset:27648
	s_waitcnt vmcnt(9)
	ds_write_b128 v89, v[104:107] offset:13824
	s_waitcnt vmcnt(8)
	ds_write_b128 v89, v[148:151] offset:32256
	v_mfma_f32_32x32x16_bf16 v[16:31], v[136:139], v[132:135], v[16:31]
	ds_read_b128 v[92:95], v82 offset:36864
	ds_read_b128 v[96:99], v81 offset:55296
	ds_read_b128 v[100:103], v82 offset:36896
	ds_read_b128 v[104:107], v81 offset:55328
	ds_read_b128 v[108:111], v81 offset:59904
	ds_read_b128 v[132:135], v81 offset:59936
	s_movk_i32 s0, 0x210
	s_add_i32 s36, s12, s52
	s_ashr_i32 s37, s36, 31
	s_lshl_b64 s[44:45], s[36:37], 24
	s_lshl_b64 s[42:43], s[36:37], 20
	s_waitcnt lgkmcnt(4)
	v_mfma_f32_32x32x16_bf16 v[32:47], v[92:95], v[96:99], v[32:47]
	s_waitcnt lgkmcnt(1)
	v_mfma_f32_32x32x16_bf16 v[48:63], v[92:95], v[108:111], v[48:63]
	ds_read_b128 v[92:95], v82 offset:41472
	ds_read_b128 v[136:139], v82 offset:41504
	s_waitcnt lgkmcnt(1)
	v_mfma_f32_32x32x16_bf16 v[0:15], v[92:95], v[96:99], v[0:15]
	v_mfma_f32_32x32x16_bf16 v[16:31], v[92:95], v[108:111], v[16:31]
	v_mfma_f32_32x32x16_bf16 v[32:47], v[100:103], v[104:107], v[32:47]
	v_mfma_f32_32x32x16_bf16 v[48:63], v[100:103], v[132:135], v[48:63]
	s_waitcnt lgkmcnt(0)
	v_mfma_f32_32x32x16_bf16 v[0:15], v[136:139], v[104:107], v[0:15]
	ds_read_b128 v[92:95], v82 offset:36928
	ds_read_b128 v[96:99], v81 offset:55360
	ds_read_b128 v[100:103], v82 offset:36960
	ds_read_b128 v[104:107], v81 offset:55392
	v_mfma_f32_32x32x16_bf16 v[16:31], v[136:139], v[132:135], v[16:31]
	ds_read_b128 v[108:111], v81 offset:59968
	ds_read_b128 v[132:135], v81 offset:60000
	s_waitcnt lgkmcnt(4)
	v_mfma_f32_32x32x16_bf16 v[32:47], v[92:95], v[96:99], v[32:47]
	s_waitcnt lgkmcnt(1)
	v_mfma_f32_32x32x16_bf16 v[48:63], v[92:95], v[108:111], v[48:63]
	ds_read_b128 v[92:95], v82 offset:41536
	ds_read_b128 v[136:139], v82 offset:41568
	s_waitcnt lgkmcnt(0)
	s_barrier
; #define G_LOAD(RA, RW, kt_) { _Pragma("unroll") for (int i = 0; i < 4; i++) { \
;       RA[i] = *(const u32x4*)(A + (aoff + (unsigned)(i * 32 * lda) + (unsigned)((kt_) * 64))); \
;       if (i < 2 * NI) RW[i] = *(const u32x4*)(W + (woff + (unsigned)(i * 32 * ldw) + (unsigned)((kt_) * 64))); } }
; #define G_STORE(RA, RW, buf_) { u16* dA = sA0 + (buf_) * GBUF; u16* dW = sW0 + (buf_) * GBUF; _Pragma("unroll") for (int i = 0; i < 4; i++) { \
;       *(u32x4*)(dA + (lr + i * 32) * 72 + lc * 8) = RA[i]; \
;       if (i < 2 * NI) *(u32x4*)(dW + (lr + i * 32) * 72 + lc * 8) = RW[i]; } }
; template <int NI>
; DI void gemm_core(f32x16 (&acc)[2][NI], const u16* __restrict__ A, int lda, const u16* __restrict__ W, int ldw, int K,
;                   u16* sA0, u16* sW0) {
;     ...
;   const int nk = K >> 6;
;   G_LOAD(raA, rwA, 0)
;   G_STORE(raA, rwA, 0)
;   G_LOAD(raA, rwA, 1)
;   if (nk > 2) G_LOAD(raB, rwB, 2)
;   __syncthreads();
;   for (int kt = 0; kt < nk; kt += 2) {
;     G_STORE(raA, rwA, 1)
;     if (kt + 3 < nk) G_LOAD(raA, rwA, kt + 3)
;     G_COMPUTE(0)
;     __syncthreads();
;     if (kt + 2 < nk) G_STORE(raB, rwB, 0)
;     if (kt + 4 < nk) G_LOAD(raB, rwB, kt + 4)
;     G_COMPUTE(1)
;     __syncthreads();
	s_waitcnt vmcnt(7)
	ds_write_b128 v89, v[112:115] offset:36864
	s_waitcnt vmcnt(5)
	ds_write_b128 v89, v[84:87] offset:55296
	ds_write_b128 v89, v[116:119] offset:41472
	s_waitcnt vmcnt(4)
	ds_write_b128 v89, v[120:123] offset:59904
	s_waitcnt vmcnt(3)
	ds_write_b128 v89, v[128:131] offset:46080
	s_waitcnt vmcnt(2)
	ds_write_b128 v89, v[124:127] offset:64512
	s_waitcnt vmcnt(1)
	ds_write_b128 v89, v[152:155] offset:50688
	s_waitcnt vmcnt(0)
	ds_write_b128 v90, v[156:159] offset:13824
	v_mfma_f32_32x32x16_bf16 v[0:15], v[92:95], v[96:99], v[0:15]
	v_mfma_f32_32x32x16_bf16 v[16:31], v[92:95], v[108:111], v[16:31]
	v_mfma_f32_32x32x16_bf16 v[32:47], v[100:103], v[104:107], v[32:47]
	v_mfma_f32_32x32x16_bf16 v[48:63], v[100:103], v[132:135], v[48:63]
	ds_read_b128 v[84:87], v82
	ds_read_b128 v[90:93], v81 offset:18432
	ds_read_b128 v[94:97], v82 offset:32
	ds_read_b128 v[98:101], v81 offset:18464
	v_mfma_f32_32x32x16_bf16 v[0:15], v[136:139], v[104:107], v[0:15]
	ds_read_b128 v[102:105], v81 offset:23040
	ds_read_b128 v[106:109], v81 offset:23072
	v_mfma_f32_32x32x16_bf16 v[16:31], v[136:139], v[132:135], v[16:31]
	s_waitcnt lgkmcnt(4)
	v_mfma_f32_32x32x16_bf16 v[32:47], v[84:87], v[90:93], v[32:47]
	s_waitcnt lgkmcnt(1)
	v_mfma_f32_32x32x16_bf16 v[48:63], v[84:87], v[102:105], v[48:63]
	ds_read_b128 v[84:87], v82 offset:4608
	ds_read_b128 v[110:113], v82 offset:4640
	s_waitcnt lgkmcnt(1)
	v_mfma_f32_32x32x16_bf16 v[0:15], v[84:87], v[90:93], v[0:15]
	v_mfma_f32_32x32x16_bf16 v[16:31], v[84:87], v[102:105], v[16:31]
	v_mfma_f32_32x32x16_bf16 v[32:47], v[94:97], v[98:101], v[32:47]
	v_mfma_f32_32x32x16_bf16 v[48:63], v[94:97], v[106:109], v[48:63]
	s_waitcnt lgkmcnt(0)
	v_mfma_f32_32x32x16_bf16 v[0:15], v[110:113], v[98:101], v[0:15]
	ds_read_b128 v[84:87], v82 offset:64
	ds_read_b128 v[90:93], v81 offset:18496
	ds_read_b128 v[94:97], v82 offset:96
	ds_read_b128 v[98:101], v81 offset:18528
	v_mfma_f32_32x32x16_bf16 v[16:31], v[110:113], v[106:109], v[16:31]
	ds_read_b128 v[102:105], v81 offset:23104
	ds_read_b128 v[106:109], v81 offset:23136
	s_waitcnt lgkmcnt(4)
	v_mfma_f32_32x32x16_bf16 v[32:47], v[84:87], v[90:93], v[32:47]
	s_waitcnt lgkmcnt(1)
	v_mfma_f32_32x32x16_bf16 v[48:63], v[84:87], v[102:105], v[48:63]
	ds_read_b128 v[84:87], v82 offset:4672
	ds_read_b128 v[110:113], v82 offset:4704
	s_waitcnt lgkmcnt(0)
	s_barrier
	v_mfma_f32_32x32x16_bf16 v[0:15], v[84:87], v[90:93], v[0:15]
	v_mfma_f32_32x32x16_bf16 v[16:31], v[84:87], v[102:105], v[16:31]
	v_mfma_f32_32x32x16_bf16 v[32:47], v[94:97], v[98:101], v[32:47]
	v_mfma_f32_32x32x16_bf16 v[48:63], v[94:97], v[106:109], v[48:63]
	v_mfma_f32_32x32x16_bf16 v[0:15], v[110:113], v[98:101], v[0:15]
	ds_read_b128 v[84:87], v82 offset:36864
	ds_read_b128 v[90:93], v81 offset:55296
	ds_read_b128 v[94:97], v82 offset:36896
	ds_read_b128 v[98:101], v81 offset:55328
	v_mfma_f32_32x32x16_bf16 v[16:31], v[110:113], v[106:109], v[16:31]
	ds_read_b128 v[102:105], v81 offset:59904
	ds_read_b128 v[106:109], v81 offset:59936
	s_waitcnt lgkmcnt(4)
	v_mfma_f32_32x32x16_bf16 v[32:47], v[84:87], v[90:93], v[32:47]
	s_waitcnt lgkmcnt(1)
	v_mfma_f32_32x32x16_bf16 v[48:63], v[84:87], v[102:105], v[48:63]
	ds_read_b128 v[84:87], v82 offset:41472
	ds_read_b128 v[110:113], v82 offset:41504
	s_waitcnt lgkmcnt(1)
	v_mfma_f32_32x32x16_bf16 v[0:15], v[84:87], v[90:93], v[0:15]
	v_mfma_f32_32x32x16_bf16 v[16:31], v[84:87], v[102:105], v[16:31]
	v_mfma_f32_32x32x16_bf16 v[32:47], v[94:97], v[98:101], v[32:47]
	v_mfma_f32_32x32x16_bf16 v[48:63], v[94:97], v[106:109], v[48:63]
	s_waitcnt lgkmcnt(0)
	v_mfma_f32_32x32x16_bf16 v[0:15], v[110:113], v[98:101], v[0:15]
	ds_read_b128 v[84:87], v82 offset:36928
	ds_read_b128 v[90:93], v81 offset:55360
	ds_read_b128 v[94:97], v82 offset:36960
	ds_read_b128 v[98:101], v81 offset:55392
	v_mfma_f32_32x32x16_bf16 v[16:31], v[110:113], v[106:109], v[16:31]
	ds_read_b128 v[102:105], v81 offset:59968
	ds_read_b128 v[106:109], v81 offset:60000
	s_waitcnt lgkmcnt(4)
	v_mfma_f32_32x32x16_bf16 v[32:47], v[84:87], v[90:93], v[32:47]
	s_waitcnt lgkmcnt(1)
	v_mfma_f32_32x32x16_bf16 v[48:63], v[84:87], v[102:105], v[48:63]
	ds_read_b128 v[84:87], v82 offset:41536
	ds_read_b128 v[110:113], v82 offset:41568
	s_waitcnt lgkmcnt(0)
	s_barrier
; DI int otid() { int t; asm volatile("v_mov_b32 %0, %1" : "=v"(t) : "v"((int)threadIdx.x)); return t; }
; template <int NI>
; DI void dump_acc(const f32x16 (&acc)[2][NI], float* sC) {
;   const int tid = otid(), lane = tid & 63, wv = tid >> 6, wm = wv >> 1, wn = wv & 1;
;   const int r = lane & 31, h = lane >> 5;
; #pragma unroll
;   for (int mi = 0; mi < 2; mi++)
; #pragma unroll
;     for (int ni = 0; ni < NI; ni++)
; #pragma unroll
;       for (int i = 0; i < 16; i++) {
;         int row = wm * 64 + mi * 32 + (i & 3) + 8 * (i >> 2) + 4 * h;
;         int col = wn * 32 * NI + ni * 32 + r;
;         sC[row * CP + col] = acc[mi][ni][i];
;       }
; DI void phase_outproj(const Params& p, int l, int half, char* smem) {
;     ...
;     dump_acc<2>(acc, sC);
;     __syncthreads();
;     const float* gate = p.mod + ((long)l * 9 + (qb < 2 ? 8 : b)) * 3072 + 2048 + tn * 128;
; #pragma unroll
;     for (int ps = 0; ps < 8; ps++) {
;       int row = (tid >> 4) + 16 * ps, ch = tid & 15;
;       int t = qb * 128 + row;
;       const float* s = sC + row * CP + ch * 8;
;       const float* xr = xrow(p, l, b, t) + tn * 128 + ch * 8;
	v_mov_b32 v81, v198
	s_nop 0
	v_lshrrev_b32_e32 v83, 3, v81
	v_mfma_f32_32x32x16_bf16 v[32:47], v[94:97], v[98:101], v[32:47]
	v_lshrrev_b32_e32 v82, 1, v81
	v_and_b32_e32 v83, 4, v83
	v_and_or_b32 v82, v82, s22, v83
	v_and_b32_e32 v81, 0x5f, v81
	v_mul_lo_u32 v82, v82, s0
	v_lshl_add_u32 v81, v81, 2, v82
	s_movk_i32 s0, 0xff
	v_mfma_f32_32x32x16_bf16 v[48:63], v[94:97], v[106:109], v[48:63]
	s_nop 11
	ds_write2_b32 v81, v32, v48 offset1:32
	ds_write2_b32 v81, v33, v49 offset0:132 offset1:164
	v_mfma_f32_32x32x16_bf16 v[0:15], v[84:87], v[90:93], v[0:15]
	v_add_u32_e32 v32, 0x400, v81
	ds_write2_b32 v32, v34, v50 offset0:8 offset1:40
	ds_write2_b32 v32, v35, v51 offset0:140 offset1:172
	v_add_u32_e32 v32, 0x1000, v81
	ds_write2_b32 v32, v36, v52 offset0:32 offset1:64
	ds_write2_b32 v32, v37, v53 offset0:164 offset1:196
	v_add_u32_e32 v32, 0x1400, v81
	ds_write2_b32 v32, v38, v54 offset0:40 offset1:72
	ds_write2_b32 v32, v39, v55 offset0:172 offset1:204
	v_add_u32_e32 v32, 0x2000, v81
	v_mfma_f32_32x32x16_bf16 v[16:31], v[84:87], v[102:105], v[16:31]
	ds_write2_b32 v32, v40, v56 offset0:64 offset1:96
	ds_write2_b32 v32, v41, v57 offset0:196 offset1:228
	v_add_u32_e32 v32, 0x2400, v81
	ds_write2_b32 v32, v42, v58 offset0:72 offset1:104
	ds_write2_b32 v32, v43, v59 offset0:204 offset1:236
	v_add_u32_e32 v32, 0x3000, v81
	ds_write2_b32 v32, v44, v60 offset0:96 offset1:128
	v_add_u32_e32 v32, 0x3200, v81
	ds_write2_b32 v32, v45, v61 offset0:100 offset1:132
	v_mfma_f32_32x32x16_bf16 v[0:15], v[110:113], v[98:101], v[0:15]
	v_add_u32_e32 v32, 0x3400, v81
	ds_write2_b32 v32, v46, v62 offset0:104 offset1:136
	v_add_u32_e32 v32, 0x3600, v81
	ds_write2_b32 v32, v47, v63 offset0:108 offset1:140
	v_add_u32_e32 v32, 0x4000, v81
	v_mfma_f32_32x32x16_bf16 v[16:31], v[110:113], v[106:109], v[16:31]
	s_nop 11
	ds_write2_b32 v32, v0, v16 offset0:128 offset1:160
	v_add_u32_e32 v0, 0x4400, v81
	ds_write2_b32 v0, v1, v17 offset0:4 offset1:36
	ds_write2_b32 v0, v2, v18 offset0:136 offset1:168
	v_add_u32_e32 v0, 0x4800, v81
	ds_write2_b32 v0, v3, v19 offset0:12 offset1:44
	v_add_u32_e32 v0, 0x5000, v81
	ds_write2_b32 v0, v4, v20 offset0:160 offset1:192
	v_add_u32_e32 v0, 0x5400, v81
	ds_write2_b32 v0, v5, v21 offset0:36 offset1:68
	ds_write2_b32 v0, v6, v22 offset0:168 offset1:200
	v_add_u32_e32 v0, 0x5800, v81
	ds_write2_b32 v0, v7, v23 offset0:44 offset1:76
	v_add_u32_e32 v0, 0x6000, v81
	ds_write2_b32 v0, v8, v24 offset0:192 offset1:224
	v_add_u32_e32 v0, 0x6400, v81
	ds_write2_b32 v0, v9, v25 offset0:68 offset1:100
	ds_write2_b32 v0, v10, v26 offset0:200 offset1:232
	v_add_u32_e32 v0, 0x6800, v81
	ds_write2_b32 v0, v11, v27 offset0:76 offset1:108
	v_add_u32_e32 v0, 0x7200, v81
	ds_write2_b32 v0, v12, v28 offset0:96 offset1:128
	v_add_u32_e32 v0, 0x7400, v81
	ds_write2_b32 v0, v13, v29 offset0:100 offset1:132
	v_add_u32_e32 v0, 0x7600, v81
	ds_write2_b32 v0, v14, v30 offset0:104 offset1:136
	v_add_u32_e32 v0, 0x7800, v81
	ds_write2_b32 v0, v15, v31 offset0:108 offset1:140
	v_add_u32_e32 v0, s57, v64
	v_cmp_lt_i32_e64 s[0:1], s0, v0
	s_waitcnt lgkmcnt(0)
	s_barrier
	s_cbranch_vccz .LBB0_47
	s_and_saveexec_b64 s[46:47], s[0:1]
	s_xor_b64 s[46:47], exec, s[46:47]
	s_cbranch_execz .LBB0_44
	v_readlane_b32 s72, v252, 38
	v_readlane_b32 s84, v252, 50
	v_add_u32_e32 v176, 0xffffff00, v0
	v_readlane_b32 s85, v252, 51
	s_add_u32 s12, s84, s44
	v_readlane_b32 s73, v252, 39
	v_readlane_b32 s74, v252, 40
	v_readlane_b32 s75, v252, 41
	v_readlane_b32 s76, v252, 42
	v_readlane_b32 s77, v252, 43
	v_readlane_b32 s78, v252, 44
	v_readlane_b32 s79, v252, 45
	v_readlane_b32 s80, v252, 46
	v_readlane_b32 s81, v252, 47
	v_readlane_b32 s82, v252, 48
	v_readlane_b32 s83, v252, 49
	v_readlane_b32 s86, v252, 52
	v_readlane_b32 s87, v252, 53
	s_addc_u32 s13, s85, s45
	v_mov_b64_e32 v[2:3], v[176:177]

; #define G_LOAD(RA, RW, kt_) { _Pragma("unroll") for (int i = 0; i < 4; i++) { \
;       RA[i] = *(const u32x4*)(A + (aoff + (unsigned)(i * 32 * lda) + (unsigned)((kt_) * 64))); \
;       if (i < 2 * NI) RW[i] = *(const u32x4*)(W + (woff + (unsigned)(i * 32 * ldw) + (unsigned)((kt_) * 64))); } }
; #define G_STORE(RA, RW, buf_) { u16* dA = sA0 + (buf_) * GBUF; u16* dW = sW0 + (buf_) * GBUF; _Pragma("unroll") for (int i = 0; i < 4; i++) { \
;       *(u32x4*)(dA + (lr + i * 32) * 72 + lc * 8) = RA[i]; \
;       if (i < 2 * NI) *(u32x4*)(dW + (lr + i * 32) * 72 + lc * 8) = RW[i]; } }
; template <int NI>
; DI void gemm_core(f32x16 (&acc)[2][NI], const u16* __restrict__ A, int lda, const u16* __restrict__ W, int ldw, int K,
;                   u16* sA0, u16* sW0) {
;     ...
;   const int nk = K >> 6;
;   G_LOAD(raA, rwA, 0)
;   G_STORE(raA, rwA, 0)
;   G_LOAD(raA, rwA, 1)
;   if (nk > 2) G_LOAD(raB, rwB, 2)
; DI void phase_merge(const Params& p, int l, int half, char* smem) {
;     ...
;   for (int it = blockIdx.x; it < ntiles; it += gridDim.x) {
;     int tmi = it >> 3, tn = it & 7;
;     int bb = tmi / nq, qb = tmi % nq + (34 - nq);
;     long mh0 = (long)bb * T + qb * 128;
;     float y[8][8];
; #pragma unroll
;     for (int a = 0; a < 8; a++)
; #pragma unroll
;       for (int b = 0; b < 8; b++) y[a][b] = 0.f;
; #pragma unroll 1
;     for (int i = 0; i < 4; i++) {
;       f32x16 acc[2][2];
;       zero_acc<2>(acc);
;       gemm_core<2>(acc, p.o + mh0 * DM + i * 256, DM, p.Wt_br + (((long)l * 4 + i) * 1024 + tn * 128) * 256, 256, 256, sA, sW);
.LBB0_142:
	s_and_b32 s0, s55, 7
	s_bfe_u32 s21, s55, 0x30006
	s_lshl_b32 s21, s21, 3
	s_add_i32 s0, s0, s21
	s_lshr_b32 s21, s55, 9
	s_lshl_b32 s21, s21, 6
	s_add_i32 s0, s0, s21
	s_abs_i32 s21, s0
	s_mul_hi_u32 s26, s21, s52
	s_mul_i32 s36, s26, s12
	s_sub_i32 s21, s21, s36
	s_ashr_i32 s1, s55, 31
	s_add_i32 s36, s26, 1
	s_sub_i32 s37, s21, s12
	s_cmp_ge_u32 s21, s12
	s_cselect_b32 s26, s36, s26
	s_cselect_b32 s21, s37, s21
	s_add_i32 s36, s26, 1
	s_cmp_ge_u32 s21, s12
	s_cselect_b32 s21, s36, s26
	s_xor_b32 s21, s21, s1
	s_sub_i32 s21, s21, s1
	s_mul_i32 s1, s21, s12
	s_sub_i32 s0, s0, s1
	s_sub_i32 s0, s0, s12
	s_lshl_b32 s0, s0, 7
	s_add_i32 s46, s0, 0x1100
	s_ashr_i32 s47, s46, 31
	v_lshl_add_u64 v[0:1], v[96:97], 0, s[46:47]
	v_mad_i64_i32 v[2:3], s[0:1], s21, v207, v[0:1]
	s_bfe_u32 s36, s55, 0x30003
	v_readlane_b32 s72, v255, 1
	s_lshl_b32 s0, s36, 8
	v_readlane_b32 s84, v255, 13
	v_readlane_b32 s85, v255, 14
	s_add_u32 s0, s84, s0
	v_lshlrev_b64 v[2:3], 13, v[2:3]
	s_addc_u32 s1, s85, 0
	s_mul_i32 s38, s21, 0x2200000
	v_lshl_add_u64 v[164:165], s[0:1], 0, v[2:3]
	s_mul_hi_i32 s37, s21, 0x2200000
	s_add_u32 s0, s0, s38
	v_lshlrev_b64 v[0:1], 13, v[0:1]
	s_addc_u32 s1, s1, s37
	s_mul_hi_i32 s26, s21, 0x1100
	s_mul_i32 s56, s21, 0x1100
	v_lshl_add_u64 v[178:179], s[0:1], 0, v[0:1]
	s_mul_hi_i32 s37, s21, 0x880000
	s_mul_i32 s21, s21, 0x880000
	s_lshl_b64 s[0:1], s[46:47], 11
	s_add_u32 s0, s21, s0
	s_addc_u32 s1, s37, s1
	s_add_u32 s48, s60, s0
	s_addc_u32 s49, s61, s1
	s_lshl_b32 s0, s36, 16
	s_add_u32 s57, s53, s0
	v_mov_b32_e32 v170, 0
	s_addc_u32 s58, s54, 0
	s_mov_b64 s[50:51], 0
	v_mov_b32_e32 v171, v170
	v_mov_b32_e32 v180, v170
	v_mov_b32_e32 v181, v170
	v_mov_b32_e32 v182, v170
	v_mov_b32_e32 v183, v170
	v_mov_b32_e32 v184, v170
	v_mov_b32_e32 v185, v170
	v_mov_b32_e32 v160, v170
	v_mov_b32_e32 v161, v170
	v_mov_b32_e32 v166, v170
	v_mov_b32_e32 v167, v170
	v_mov_b32_e32 v172, v170
	v_mov_b32_e32 v173, v170
	v_mov_b32_e32 v174, v170
	v_mov_b32_e32 v175, v170
	v_mov_b32_e32 v152, v170
	v_mov_b32_e32 v153, v170
	v_mov_b32_e32 v156, v170
	v_mov_b32_e32 v157, v170
	v_mov_b32_e32 v162, v170
	v_mov_b32_e32 v163, v170
	v_mov_b32_e32 v168, v170
	v_mov_b32_e32 v169, v170
	v_mov_b32_e32 v144, v170
	v_mov_b32_e32 v145, v170
	v_mov_b32_e32 v148, v170
	v_mov_b32_e32 v149, v170
	v_mov_b32_e32 v154, v170
	v_mov_b32_e32 v155, v170
	v_mov_b32_e32 v158, v170
	v_mov_b32_e32 v159, v170
	v_mov_b32_e32 v136, v170
	v_mov_b32_e32 v137, v170
	v_mov_b32_e32 v140, v170
	v_mov_b32_e32 v141, v170
	v_mov_b32_e32 v146, v170
	v_mov_b32_e32 v147, v170
	v_mov_b32_e32 v150, v170
	v_mov_b32_e32 v151, v170
	v_mov_b32_e32 v128, v170
	v_mov_b32_e32 v129, v170
	v_mov_b32_e32 v132, v170
	v_mov_b32_e32 v133, v170
	v_mov_b32_e32 v138, v170
	v_mov_b32_e32 v139, v170
	v_mov_b32_e32 v142, v170
	v_mov_b32_e32 v143, v170
	v_mov_b32_e32 v120, v170
	v_mov_b32_e32 v121, v170
	v_mov_b32_e32 v124, v170
	v_mov_b32_e32 v125, v170
	v_mov_b32_e32 v130, v170
	v_mov_b32_e32 v131, v170
	v_mov_b32_e32 v134, v170
	v_mov_b32_e32 v135, v170
	v_mov_b32_e32 v116, v170
	v_mov_b32_e32 v117, v170
	v_mov_b32_e32 v118, v170
	v_mov_b32_e32 v119, v170
	v_mov_b32_e32 v122, v170
	v_mov_b32_e32 v123, v170
	v_mov_b32_e32 v126, v170
	v_mov_b32_e32 v127, v170
	s_movk_i32 s59, 0x210
	v_readlane_b32 s73, v255, 2
	v_readlane_b32 s74, v255, 3
	v_readlane_b32 s75, v255, 4
	v_readlane_b32 s76, v255, 5
	v_readlane_b32 s77, v255, 6
	v_readlane_b32 s78, v255, 7
	v_readlane_b32 s79, v255, 8
	v_readlane_b32 s80, v255, 9
	v_readlane_b32 s81, v255, 10
	v_readlane_b32 s82, v255, 11
	v_readlane_b32 s83, v255, 12
	v_readlane_b32 s86, v255, 15
	v_readlane_b32 s87, v255, 16
.LBB0_143:
	v_mov_b32 v0, v198
	s_add_u32 s0, s57, s50
	v_lshlrev_b32_e32 v4, 3, v0
	v_ashrrev_i32_e32 v2, 3, v0
	v_and_b32_e32 v6, 31, v0
	s_waitcnt vmcnt(1)
	v_lshrrev_b32_e32 v8, 1, v0
	v_and_b32_e32 v4, 56, v4
	v_mov_b32_e32 v1, v177
	v_and_b32_e32 v10, 0x5f, v0
	s_waitcnt vmcnt(0)
	v_mul_lo_u32 v12, v2, s23
	v_and_or_b32 v6, v8, s22, v6
	v_and_b32_e32 v0, 16, v8
	v_lshl_or_b32 v176, v2, 10, v4
	v_lshl_or_b32 v188, v2, 8, v4
	v_mov_b32_e32 v189, v177
	v_mov_b32_e32 v3, v177
	v_mov_b32_e32 v5, v177
	v_mov_b32_e32 v7, v177
	v_mov_b32_e32 v9, v177
	v_mov_b32_e32 v11, v177
	s_addc_u32 s1, s58, s51
	v_lshl_add_u32 v191, v4, 1, v12
	v_mad_u64_u32 v[186:187], s[36:37], v6, s23, v[0:1]
	v_mad_u32_u24 v115, v10, s23, v0
	v_lshl_add_u64 v[196:197], v[176:177], 1, s[48:49]
	v_add_u32_e32 v0, 0x8000, v176
	v_add_u32_e32 v2, 0x2000, v188
	v_add_u32_e32 v4, 0x10000, v176
	v_add_u32_e32 v6, 0x4000, v188
	v_add_u32_e32 v8, 0x18000, v176
	v_add_u32_e32 v10, 0x6000, v188
	v_lshl_add_u64 v[202:203], v[188:189], 1, s[0:1]
	v_lshl_add_u64 v[40:41], v[0:1], 1, s[48:49]
	v_lshl_add_u64 v[42:43], v[2:3], 1, s[0:1]
	v_lshl_add_u64 v[44:45], v[4:5], 1, s[48:49]
	v_lshl_add_u64 v[46:47], v[6:7], 1, s[0:1]
	v_lshl_add_u64 v[48:49], v[8:9], 1, s[48:49]
	v_lshl_add_u64 v[50:51], v[10:11], 1, s[0:1]
	global_load_dwordx4 v[0:3], v[196:197], off offset:-384
	global_load_dwordx4 v[4:7], v[196:197], off offset:-256
	global_load_dwordx4 v[8:11], v[202:203], off
	global_load_dwordx4 v[12:15], v[202:203], off offset:128
	v_mov_b32_e32 v17, v177
	v_mov_b32_e32 v19, v177
	v_mov_b32_e32 v21, v177
	v_mov_b32_e32 v23, v177
	v_mov_b32_e32 v25, v177
	v_mov_b32_e32 v27, v177
	v_mov_b32_e32 v29, v177
	v_mov_b32_e32 v31, v177
	v_mov_b32_e32 v33, v177
	v_mov_b32_e32 v35, v177
	v_mov_b32_e32 v37, v177
	v_mov_b32_e32 v39, v177
	v_add_u32_e32 v16, 0x8040, v176
	v_add_u32_e32 v18, 0x2040, v188
	v_add_u32_e32 v20, 0x10040, v176
	v_add_u32_e32 v22, 0x4040, v188
	v_add_u32_e32 v24, 0x18040, v176
; #define G_LOAD(RA, RW, kt_) { _Pragma("unroll") for (int i = 0; i < 4; i++) { \
;       RA[i] = *(const u32x4*)(A + (aoff + (unsigned)(i * 32 * lda) + (unsigned)((kt_) * 64))); \
;       if (i < 2 * NI) RW[i] = *(const u32x4*)(W + (woff + (unsigned)(i * 32 * ldw) + (unsigned)((kt_) * 64))); } }
; #define G_STORE(RA, RW, buf_) { u16* dA = sA0 + (buf_) * GBUF; u16* dW = sW0 + (buf_) * GBUF; _Pragma("unroll") for (int i = 0; i < 4; i++) { \
;       *(u32x4*)(dA + (lr + i * 32) * 72 + lc * 8) = RA[i]; \
;       if (i < 2 * NI) *(u32x4*)(dW + (lr + i * 32) * 72 + lc * 8) = RW[i]; } }
; template <int NI>
; DI void gemm_core(f32x16 (&acc)[2][NI], const u16* __restrict__ A, int lda, const u16* __restrict__ W, int ldw, int K,
;                   u16* sA0, u16* sW0) {
;     ...
;   const int nk = K >> 6;
;   G_LOAD(raA, rwA, 0)
;   G_STORE(raA, rwA, 0)
;   G_LOAD(raA, rwA, 1)
;   if (nk > 2) G_LOAD(raB, rwB, 2)
;   __syncthreads();
;   for (int kt = 0; kt < nk; kt += 2) {
;     G_STORE(raA, rwA, 1)
;     if (kt + 3 < nk) G_LOAD(raA, rwA, kt + 3)
;     G_COMPUTE(0)
;     __syncthreads();
;     if (kt + 2 < nk) G_STORE(raB, rwB, 0)
;     if (kt + 4 < nk) G_LOAD(raB, rwB, kt + 4)
;     G_COMPUTE(1)
;     __syncthreads();
	v_add_u32_e32 v26, 0x6040, v188
	v_add_u32_e32 v28, 0x8080, v176
	v_add_u32_e32 v30, 0x2080, v188
	v_add_u32_e32 v32, 0x10080, v176
	v_add_u32_e32 v34, 0x4080, v188
	v_add_u32_e32 v36, 0x18080, v176
	v_add_u32_e32 v38, 0x6080, v188
	v_lshl_add_u64 v[52:53], v[16:17], 1, s[48:49]
	v_lshl_add_u64 v[54:55], v[18:19], 1, s[0:1]
	v_lshl_add_u64 v[56:57], v[20:21], 1, s[48:49]
	v_lshl_add_u64 v[58:59], v[22:23], 1, s[0:1]
	v_lshl_add_u64 v[60:61], v[24:25], 1, s[48:49]
	v_lshl_add_u64 v[62:63], v[26:27], 1, s[0:1]
	v_lshl_add_u64 v[72:73], v[28:29], 1, s[48:49]
	v_lshl_add_u64 v[76:77], v[30:31], 1, s[0:1]
	v_lshl_add_u64 v[80:81], v[32:33], 1, s[48:49]
	v_lshl_add_u64 v[84:85], v[34:35], 1, s[0:1]
	v_lshl_add_u64 v[88:89], v[36:37], 1, s[48:49]
	v_lshl_add_u64 v[92:93], v[38:39], 1, s[0:1]
	global_load_dwordx4 v[68:71], v[196:197], off offset:-128
	global_load_dwordx4 v[64:67], v[202:203], off offset:256
	global_load_dwordx4 v[16:19], v[40:41], off offset:-384
	global_load_dwordx4 v[20:23], v[42:43], off
	global_load_dwordx4 v[24:27], v[44:45], off offset:-384
	global_load_dwordx4 v[28:31], v[46:47], off
	global_load_dwordx4 v[32:35], v[48:49], off offset:-384
	global_load_dwordx4 v[36:39], v[50:51], off
	s_nop 0
	global_load_dwordx4 v[40:43], v[52:53], off offset:-384
	global_load_dwordx4 v[44:47], v[54:55], off
	global_load_dwordx4 v[48:51], v[56:57], off offset:-384
	s_nop 0
	global_load_dwordx4 v[52:55], v[58:59], off
	s_nop 0
	global_load_dwordx4 v[56:59], v[60:61], off offset:-384
	s_nop 0
	global_load_dwordx4 v[60:63], v[62:63], off
	s_nop 0
	global_load_dwordx4 v[72:75], v[72:73], off offset:-384
	s_nop 0
	global_load_dwordx4 v[76:79], v[76:77], off
	s_nop 0
	global_load_dwordx4 v[80:83], v[80:81], off offset:-384
	s_nop 0
	global_load_dwordx4 v[84:87], v[84:85], off
	s_nop 0
	global_load_dwordx4 v[88:91], v[88:89], off offset:-384
	s_nop 0
	global_load_dwordx4 v[92:95], v[92:93], off
	v_add_u32_e32 v187, 0xd800, v191
	v_mov_b32_e32 v211, v177
	v_mov_b32_e32 v213, v177
	v_mov_b32_e32 v229, v177
	v_add_u32_e32 v210, 0x180c0, v176
	s_waitcnt vmcnt(23)
	ds_write_b128 v191, v[0:3]
	s_waitcnt vmcnt(21)
	ds_write_b128 v191, v[8:11] offset:18432
	s_waitcnt vmcnt(17)
	ds_write_b128 v191, v[16:19] offset:4608
	s_waitcnt vmcnt(16)
	ds_write_b128 v191, v[20:23] offset:23040
	s_waitcnt vmcnt(15)
	ds_write_b128 v191, v[24:27] offset:9216
	s_waitcnt vmcnt(14)
	ds_write_b128 v191, v[28:31] offset:27648
	s_waitcnt vmcnt(13)
	ds_write_b128 v191, v[32:35] offset:13824
	s_waitcnt vmcnt(12)
	ds_write_b128 v191, v[36:39] offset:32256
	s_waitcnt lgkmcnt(0)
	s_barrier
	ds_write_b128 v191, v[4:7] offset:36864
	ds_write_b128 v191, v[12:15] offset:55296
	s_waitcnt vmcnt(11)
	ds_write_b128 v191, v[40:43] offset:41472
	s_waitcnt vmcnt(10)
	ds_write_b128 v191, v[44:47] offset:59904
	s_waitcnt vmcnt(9)
	ds_write_b128 v191, v[48:51] offset:46080
	s_waitcnt vmcnt(8)
	ds_write_b128 v191, v[52:55] offset:64512
	s_waitcnt vmcnt(7)
	ds_write_b128 v191, v[56:59] offset:50688
	s_waitcnt vmcnt(6)
	ds_write_b128 v187, v[60:63] offset:13824
	ds_read_b128 v[0:3], v186
	ds_read_b128 v[4:7], v115 offset:18432
	ds_read_b128 v[16:19], v115 offset:23040
	ds_read_b128 v[20:23], v186 offset:4608
	s_waitcnt lgkmcnt(2)
	v_mfma_f32_32x32x16_bf16 v[32:47], v[0:3], v[4:7], 0
	ds_read_b128 v[192:195], v186 offset:32
	ds_read_b128 v[220:223], v115 offset:18464
	ds_read_b128 v[224:227], v115 offset:23072
	v_add_u32_e32 v212, 0x40c0, v188
	v_add_u32_e32 v228, 0x100c0, v176
	v_add_u32_e32 v176, 0x80c0, v176
	v_mov_b32_e32 v205, v177
	v_add_u32_e32 v204, 0x60c0, v188
	s_waitcnt lgkmcnt(4)
	v_mfma_f32_32x32x16_bf16 v[48:63], v[0:3], v[16:19], 0
	v_add_u32_e32 v188, 0x20c0, v188
	v_lshl_add_u64 v[210:211], v[210:211], 1, s[48:49]
	v_lshl_add_u64 v[212:213], v[212:213], 1, s[0:1]
	v_lshl_add_u64 v[240:241], v[228:229], 1, s[48:49]
	v_lshl_add_u64 v[232:233], v[176:177], 1, s[48:49]
	v_lshl_add_u64 v[204:205], v[204:205], 1, s[0:1]
	v_lshl_add_u64 v[188:189], v[188:189], 1, s[0:1]
	s_waitcnt lgkmcnt(1)
	v_mfma_f32_32x32x16_bf16 v[32:47], v[192:195], v[220:223], v[32:47]
	s_mov_b32 s0, 0x20000
	s_mov_b32 s21, 0xa0000
	s_add_u32 s50, s50, 0x80000
	s_addc_u32 s51, s51, 0
	s_add_u32 s48, s48, 0x200
	s_addc_u32 s49, s49, 0
	s_cmp_eq_u32 s50, 0x200000
	s_waitcnt lgkmcnt(0)
	v_mfma_f32_32x32x16_bf16 v[48:63], v[192:195], v[224:227], v[48:63]
	ds_read_b128 v[192:195], v186 offset:4640
	v_mfma_f32_32x32x16_bf16 v[0:15], v[20:23], v[4:7], 0
	v_mfma_f32_32x32x16_bf16 v[16:31], v[20:23], v[16:19], 0
	s_waitcnt lgkmcnt(0)
	v_mfma_f32_32x32x16_bf16 v[0:15], v[192:195], v[220:223], v[0:15]
	v_mfma_f32_32x32x16_bf16 v[16:31], v[192:195], v[224:227], v[16:31]
	ds_read_b128 v[192:195], v186 offset:64
	ds_read_b128 v[220:223], v115 offset:18496
	ds_read_b128 v[224:227], v115 offset:23104
	s_waitcnt lgkmcnt(1)
	v_mfma_f32_32x32x16_bf16 v[32:47], v[192:195], v[220:223], v[32:47]
	s_waitcnt lgkmcnt(0)
	v_mfma_f32_32x32x16_bf16 v[48:63], v[192:195], v[224:227], v[48:63]
	ds_read_b128 v[192:195], v186 offset:4672
	s_waitcnt lgkmcnt(0)
	v_mfma_f32_32x32x16_bf16 v[0:15], v[192:195], v[220:223], v[0:15]
	global_load_dwordx4 v[220:223], v[196:197], off
	global_load_dwordx4 v[228:231], v[202:203], off offset:384
	s_nop 0
	global_load_dwordx4 v[232:235], v[232:233], off offset:-384
	s_nop 0
	global_load_dwordx4 v[236:239], v[188:189], off
	s_nop 0
	global_load_dwordx4 v[240:243], v[240:241], off offset:-384
	s_nop 0
	global_load_dwordx4 v[244:247], v[212:213], off
	v_mfma_f32_32x32x16_bf16 v[16:31], v[192:195], v[224:227], v[16:31]
	ds_read_b128 v[192:195], v186 offset:96
	ds_read_b128 v[224:227], v115 offset:18528
	global_load_dwordx4 v[248:251], v[210:211], off offset:-384
	s_nop 0
	global_load_dwordx4 v[210:213], v[204:205], off
	ds_read_b128 v[202:205], v115 offset:23136
	s_waitcnt lgkmcnt(1)
	v_mfma_f32_32x32x16_bf16 v[32:47], v[192:195], v[224:227], v[32:47]
	s_waitcnt lgkmcnt(0)
	v_mfma_f32_32x32x16_bf16 v[48:63], v[192:195], v[202:205], v[48:63]
	ds_read_b128 v[192:195], v186 offset:4704
	s_waitcnt lgkmcnt(0)
	s_barrier
; #define G_LOAD(RA, RW, kt_) { _Pragma("unroll") for (int i = 0; i < 4; i++) { \
;       RA[i] = *(const u32x4*)(A + (aoff + (unsigned)(i * 32 * lda) + (unsigned)((kt_) * 64))); \
;       if (i < 2 * NI) RW[i] = *(const u32x4*)(W + (woff + (unsigned)(i * 32 * ldw) + (unsigned)((kt_) * 64))); } }
; #define G_STORE(RA, RW, buf_) { u16* dA = sA0 + (buf_) * GBUF; u16* dW = sW0 + (buf_) * GBUF; _Pragma("unroll") for (int i = 0; i < 4; i++) { \
;       *(u32x4*)(dA + (lr + i * 32) * 72 + lc * 8) = RA[i]; \
;       if (i < 2 * NI) *(u32x4*)(dW + (lr + i * 32) * 72 + lc * 8) = RW[i]; } }
; template <int NI>
; DI void gemm_core(f32x16 (&acc)[2][NI], const u16* __restrict__ A, int lda, const u16* __restrict__ W, int ldw, int K,
;                   u16* sA0, u16* sW0) {
;     ...
;   for (int kt = 0; kt < nk; kt += 2) {
;     G_STORE(raA, rwA, 1)
;     if (kt + 3 < nk) G_LOAD(raA, rwA, kt + 3)
;     G_COMPUTE(0)
;     __syncthreads();
;     if (kt + 2 < nk) G_STORE(raB, rwB, 0)
;     if (kt + 4 < nk) G_LOAD(raB, rwB, kt + 4)
;     G_COMPUTE(1)
;     __syncthreads();
	ds_write_b128 v191, v[68:71]
	ds_write_b128 v191, v[64:67] offset:18432
	s_waitcnt vmcnt(13)
	ds_write_b128 v191, v[72:75] offset:4608
	s_waitcnt vmcnt(12)
	ds_write_b128 v191, v[76:79] offset:23040
	s_waitcnt vmcnt(11)
	ds_write_b128 v191, v[80:83] offset:9216
	s_waitcnt vmcnt(10)
	ds_write_b128 v191, v[84:87] offset:27648
	s_waitcnt vmcnt(9)
	ds_write_b128 v191, v[88:91] offset:13824
	s_waitcnt vmcnt(8)
	ds_write_b128 v191, v[92:95] offset:32256
	ds_read_b128 v[64:67], v186 offset:36864
	ds_read_b128 v[68:71], v115 offset:55296
	ds_read_b128 v[72:75], v115 offset:59904
	s_waitcnt lgkmcnt(1)
	v_mfma_f32_32x32x16_bf16 v[32:47], v[64:67], v[68:71], v[32:47]
	s_waitcnt lgkmcnt(0)
	v_mfma_f32_32x32x16_bf16 v[48:63], v[64:67], v[72:75], v[48:63]
	ds_read_b128 v[64:67], v186 offset:41472
	v_mfma_f32_32x32x16_bf16 v[0:15], v[192:195], v[224:227], v[0:15]
	v_mfma_f32_32x32x16_bf16 v[16:31], v[192:195], v[202:205], v[16:31]
	s_waitcnt lgkmcnt(0)
	v_mfma_f32_32x32x16_bf16 v[0:15], v[64:67], v[68:71], v[0:15]
	v_mfma_f32_32x32x16_bf16 v[16:31], v[64:67], v[72:75], v[16:31]
	ds_read_b128 v[64:67], v186 offset:36896
	ds_read_b128 v[68:71], v115 offset:55328
	ds_read_b128 v[72:75], v115 offset:59936
	s_waitcnt lgkmcnt(1)
	v_mfma_f32_32x32x16_bf16 v[32:47], v[64:67], v[68:71], v[32:47]
	s_waitcnt lgkmcnt(0)
	v_mfma_f32_32x32x16_bf16 v[48:63], v[64:67], v[72:75], v[48:63]
	ds_read_b128 v[64:67], v186 offset:41504
	s_waitcnt lgkmcnt(0)
	v_mfma_f32_32x32x16_bf16 v[0:15], v[64:67], v[68:71], v[0:15]
	v_mfma_f32_32x32x16_bf16 v[16:31], v[64:67], v[72:75], v[16:31]
	ds_read_b128 v[64:67], v186 offset:36928
	ds_read_b128 v[68:71], v115 offset:55360
	ds_read_b128 v[72:75], v115 offset:59968
	s_waitcnt lgkmcnt(1)
	v_mfma_f32_32x32x16_bf16 v[32:47], v[64:67], v[68:71], v[32:47]
	s_waitcnt lgkmcnt(0)
	v_mfma_f32_32x32x16_bf16 v[48:63], v[64:67], v[72:75], v[48:63]
	ds_read_b128 v[64:67], v186 offset:41536
	s_waitcnt lgkmcnt(0)
	v_mfma_f32_32x32x16_bf16 v[0:15], v[64:67], v[68:71], v[0:15]
	v_mfma_f32_32x32x16_bf16 v[16:31], v[64:67], v[72:75], v[16:31]
	ds_read_b128 v[64:67], v186 offset:36960
	ds_read_b128 v[68:71], v115 offset:55392
	ds_read_b128 v[72:75], v115 offset:60000
	s_waitcnt lgkmcnt(1)
	v_mfma_f32_32x32x16_bf16 v[32:47], v[64:67], v[68:71], v[32:47]
	s_waitcnt lgkmcnt(0)
	v_mfma_f32_32x32x16_bf16 v[48:63], v[64:67], v[72:75], v[48:63]
	ds_read_b128 v[64:67], v186 offset:41568
	s_waitcnt lgkmcnt(0)
	s_barrier
	s_waitcnt vmcnt(7)
	ds_write_b128 v191, v[220:223] offset:36864
	s_waitcnt vmcnt(6)
	ds_write_b128 v191, v[228:231] offset:55296
	s_waitcnt vmcnt(5)
	ds_write_b128 v191, v[232:235] offset:41472
	s_waitcnt vmcnt(4)
	ds_write_b128 v191, v[236:239] offset:59904
	s_waitcnt vmcnt(3)
	ds_write_b128 v191, v[240:243] offset:46080
	s_waitcnt vmcnt(2)
	ds_write_b128 v191, v[244:247] offset:64512
	s_waitcnt vmcnt(1)
	ds_write_b128 v191, v[248:251] offset:50688
	s_waitcnt vmcnt(0)
	ds_write_b128 v187, v[210:213] offset:13824
	v_mfma_f32_32x32x16_bf16 v[0:15], v[64:67], v[68:71], v[0:15]
	v_mfma_f32_32x32x16_bf16 v[16:31], v[64:67], v[72:75], v[16:31]
	ds_read_b128 v[64:67], v186
	ds_read_b128 v[68:71], v115 offset:18432
	ds_read_b128 v[72:75], v115 offset:23040
	s_waitcnt lgkmcnt(1)
	v_mfma_f32_32x32x16_bf16 v[32:47], v[64:67], v[68:71], v[32:47]
	s_waitcnt lgkmcnt(0)
	v_mfma_f32_32x32x16_bf16 v[48:63], v[64:67], v[72:75], v[48:63]
	ds_read_b128 v[64:67], v186 offset:4608
	s_waitcnt lgkmcnt(0)
	v_mfma_f32_32x32x16_bf16 v[0:15], v[64:67], v[68:71], v[0:15]
	v_mfma_f32_32x32x16_bf16 v[16:31], v[64:67], v[72:75], v[16:31]
	ds_read_b128 v[64:67], v186 offset:32
	ds_read_b128 v[68:71], v115 offset:18464
	ds_read_b128 v[72:75], v115 offset:23072
	ds_read_b128 v[76:79], v186 offset:4640
	s_waitcnt lgkmcnt(2)
	v_mfma_f32_32x32x16_bf16 v[32:47], v[64:67], v[68:71], v[32:47]
	s_waitcnt lgkmcnt(1)
	v_mfma_f32_32x32x16_bf16 v[48:63], v[64:67], v[72:75], v[48:63]
	v_lshl_add_u64 v[64:65], v[164:165], 0, v[112:113]
	v_lshl_add_u64 v[164:165], v[164:165], 0, s[66:67]
	s_waitcnt lgkmcnt(0)
	v_mfma_f32_32x32x16_bf16 v[0:15], v[76:79], v[68:71], v[0:15]
	v_mfma_f32_32x32x16_bf16 v[16:31], v[76:79], v[72:75], v[16:31]
	ds_read_b128 v[66:69], v186 offset:64
	ds_read_b128 v[74:77], v115 offset:18496
	ds_read_b128 v[78:81], v115 offset:23104
	ds_read_b128 v[82:85], v186 offset:4672
	v_lshl_add_u64 v[72:73], v[178:179], 0, v[112:113]
	v_add_co_u32_e64 v192, s[40:41], s21, v72
	s_mov_b32 s21, 0xc0000
	s_waitcnt lgkmcnt(2)
	v_mfma_f32_32x32x16_bf16 v[32:47], v[66:69], v[74:77], v[32:47]
	v_add_co_u32_e64 v194, s[42:43], s21, v72
	s_mov_b32 s21, 0xe0000
	v_add_co_u32_e64 v196, s[44:45], s21, v72
	v_lshl_add_u64 v[178:179], v[178:179], 0, s[66:67]
	s_waitcnt lgkmcnt(1)
	v_mfma_f32_32x32x16_bf16 v[48:63], v[66:69], v[78:81], v[48:63]
	v_add_co_u32_e32 v66, vcc, s0, v72
	s_mov_b32 s0, 0x40000
	v_add_co_u32_e64 v68, s[36:37], s0, v72
	s_mov_b32 s0, 0x60000
	v_add_co_u32_e64 v70, s[38:39], s0, v72
	s_waitcnt lgkmcnt(0)
	v_mfma_f32_32x32x16_bf16 v[0:15], v[82:85], v[74:77], v[0:15]
	s_mov_b32 s0, 0x80000
	v_add_co_u32_e64 v188, s[0:1], s0, v72
	v_addc_co_u32_e32 v67, vcc, 0, v73, vcc
	v_addc_co_u32_e64 v69, vcc, 0, v73, s[36:37]
	v_mfma_f32_32x32x16_bf16 v[16:31], v[82:85], v[78:81], v[16:31]
	ds_read_b128 v[74:77], v186 offset:96
	ds_read_b128 v[78:81], v115 offset:18528
	ds_read_b128 v[82:85], v115 offset:23136
	v_addc_co_u32_e64 v71, vcc, 0, v73, s[38:39]
	v_addc_co_u32_e64 v189, vcc, 0, v73, s[0:1]
	v_addc_co_u32_e64 v193, vcc, 0, v73, s[40:41]
	s_waitcnt lgkmcnt(1)
	v_mfma_f32_32x32x16_bf16 v[32:47], v[74:77], v[78:81], v[32:47]
	v_addc_co_u32_e64 v195, vcc, 0, v73, s[42:43]
	v_addc_co_u32_e64 v197, vcc, 0, v73, s[44:45]
	s_waitcnt lgkmcnt(0)
	v_mfma_f32_32x32x16_bf16 v[48:63], v[74:77], v[82:85], v[48:63]
	ds_read_b128 v[74:77], v186 offset:4704
	s_waitcnt lgkmcnt(0)
	s_barrier
; DI int otid() { int t; asm volatile("v_mov_b32 %0, %1" : "=v"(t) : "v"((int)threadIdx.x)); return t; }
; template <int NI>
; DI void dump_acc(const f32x16 (&acc)[2][NI], float* sC) {
;   const int tid = otid(), lane = tid & 63, wv = tid >> 6, wm = wv >> 1, wn = wv & 1;
;   const int r = lane & 31, h = lane >> 5;
; #pragma unroll
;   for (int mi = 0; mi < 2; mi++)
; #pragma unroll
;     for (int ni = 0; ni < NI; ni++)
; #pragma unroll
;       for (int i = 0; i < 16; i++) {
;         int row = wm * 64 + mi * 32 + (i & 3) + 8 * (i >> 2) + 4 * h;
;         int col = wn * 32 * NI + ni * 32 + r;
;         sC[row * CP + col] = acc[mi][ni][i];
;       }
; DI void phase_merge(const Params& p, int l, int half, char* smem) {
;     ...
;       for (int ps = 0; ps < 8; ps++) {
;         int row = (tid >> 4) + 16 * ps, ch = tid & 15;
;         const float* s = sC + row * CP + ch * 8;
;         f32x4v a = *(const f32x4v*)s, b = *(const f32x4v*)(s + 4);
;         u32x4 g = *(const u32x4*)(p.G + (mh0 + row) * 4096 + i * 1024 + tn * 128 + ch * 8);
	v_mfma_f32_32x32x16_bf16 v[0:15], v[74:77], v[78:81], v[0:15]
	v_mfma_f32_32x32x16_bf16 v[16:31], v[74:77], v[82:85], v[16:31]
	ds_read_b128 v[74:77], v186 offset:36864
	ds_read_b128 v[78:81], v115 offset:55296
	ds_read_b128 v[82:85], v115 offset:59904
	s_waitcnt lgkmcnt(1)
	v_mfma_f32_32x32x16_bf16 v[32:47], v[74:77], v[78:81], v[32:47]
	s_waitcnt lgkmcnt(0)
	v_mfma_f32_32x32x16_bf16 v[48:63], v[74:77], v[82:85], v[48:63]
	ds_read_b128 v[74:77], v186 offset:41472
	s_waitcnt lgkmcnt(0)
	v_mfma_f32_32x32x16_bf16 v[0:15], v[74:77], v[78:81], v[0:15]
	v_mfma_f32_32x32x16_bf16 v[16:31], v[74:77], v[82:85], v[16:31]
	ds_read_b128 v[74:77], v186 offset:36896
	ds_read_b128 v[78:81], v115 offset:55328
	ds_read_b128 v[82:85], v115 offset:59936
	s_waitcnt lgkmcnt(1)
	v_mfma_f32_32x32x16_bf16 v[32:47], v[74:77], v[78:81], v[32:47]
	s_waitcnt lgkmcnt(0)
	v_mfma_f32_32x32x16_bf16 v[48:63], v[74:77], v[82:85], v[48:63]
	ds_read_b128 v[74:77], v186 offset:41504
	s_waitcnt lgkmcnt(0)
	v_mfma_f32_32x32x16_bf16 v[0:15], v[74:77], v[78:81], v[0:15]
	v_mfma_f32_32x32x16_bf16 v[16:31], v[74:77], v[82:85], v[16:31]
	ds_read_b128 v[72:75], v186 offset:36928
	ds_read_b128 v[76:79], v115 offset:55360
	ds_read_b128 v[80:83], v115 offset:59968
	s_waitcnt lgkmcnt(1)
	v_mfma_f32_32x32x16_bf16 v[32:47], v[72:75], v[76:79], v[32:47]
	s_waitcnt lgkmcnt(0)
	v_mfma_f32_32x32x16_bf16 v[48:63], v[72:75], v[80:83], v[48:63]
	ds_read_b128 v[72:75], v186 offset:41536
	ds_read_b128 v[84:87], v115 offset:60000
	ds_read_b128 v[88:91], v115 offset:55392
	s_waitcnt lgkmcnt(2)
	v_mfma_f32_32x32x16_bf16 v[0:15], v[72:75], v[76:79], v[0:15]
	ds_read_b128 v[76:79], v186 offset:41568
	ds_read_b128 v[92:95], v186 offset:36960
	s_waitcnt lgkmcnt(0)
	s_barrier
	v_mov_b32 v115, v198
	s_nop 0
	v_lshrrev_b32_e32 v176, 1, v115
	v_mfma_f32_32x32x16_bf16 v[16:31], v[72:75], v[80:83], v[16:31]
	v_lshrrev_b32_e32 v72, 3, v115
	v_and_b32_e32 v72, 4, v72
	v_and_or_b32 v72, v176, s22, v72
	v_and_b32_e32 v73, 0x5f, v115
	v_mul_lo_u32 v72, v72, s59
	v_lshl_add_u32 v72, v73, 2, v72
	v_add_u32_e32 v73, 0x400, v72
	v_mfma_f32_32x32x16_bf16 v[32:47], v[92:95], v[88:91], v[32:47]
	v_add_u32_e32 v74, 0x1000, v72
	v_add_u32_e32 v75, 0x1400, v72
	v_add_u32_e32 v80, 0x2000, v72
	v_add_u32_e32 v81, 0x2400, v72
	v_add_u32_e32 v82, 0x3000, v72
	v_add_u32_e32 v83, 0x3200, v72
	v_add_u32_e32 v115, 0x3400, v72
	v_mfma_f32_32x32x16_bf16 v[48:63], v[92:95], v[84:87], v[48:63]
	v_add_u32_e32 v92, 0x3600, v72
	v_add_u32_e32 v93, 0x4000, v72
	v_add_u32_e32 v94, 0x4400, v72
	v_add_u32_e32 v95, 0x4800, v72
	v_add_u32_e32 v176, 0x5000, v72
	v_add_u32_e32 v186, 0x5400, v72
	v_add_u32_e32 v187, 0x5800, v72
	v_mfma_f32_32x32x16_bf16 v[0:15], v[76:79], v[88:91], v[0:15]
	v_add_u32_e32 v88, 0x6000, v72
	v_add_u32_e32 v89, 0x6400, v72
	v_add_u32_e32 v90, 0x6800, v72
	v_add_u32_e32 v91, 0x7200, v72
	v_add_u32_e32 v191, 0x7400, v72
	v_add_u32_e32 v202, 0x7600, v72
	v_add_u32_e32 v203, 0x7800, v72
	v_mfma_f32_32x32x16_bf16 v[16:31], v[76:79], v[84:87], v[16:31]
	ds_write2_b32 v72, v32, v48 offset1:32
	ds_write2_b32 v72, v33, v49 offset0:132 offset1:164
	ds_write2_b32 v73, v34, v50 offset0:8 offset1:40
	ds_write2_b32 v73, v35, v51 offset0:140 offset1:172
	ds_write2_b32 v74, v36, v52 offset0:32 offset1:64
	ds_write2_b32 v74, v37, v53 offset0:164 offset1:196
	ds_write2_b32 v75, v38, v54 offset0:40 offset1:72
	ds_write2_b32 v75, v39, v55 offset0:172 offset1:204
	ds_write2_b32 v80, v40, v56 offset0:64 offset1:96
	ds_write2_b32 v80, v41, v57 offset0:196 offset1:228
	ds_write2_b32 v81, v42, v58 offset0:72 offset1:104
	ds_write2_b32 v81, v43, v59 offset0:204 offset1:236
	ds_write2_b32 v82, v44, v60 offset0:96 offset1:128
	ds_write2_b32 v83, v45, v61 offset0:100 offset1:132
	ds_write2_b32 v115, v46, v62 offset0:104 offset1:136
	ds_write2_b32 v92, v47, v63 offset0:108 offset1:140
	ds_write2_b32 v93, v0, v16 offset0:128 offset1:160
	ds_write2_b32 v94, v1, v17 offset0:4 offset1:36
	ds_write2_b32 v94, v2, v18 offset0:136 offset1:168
	ds_write2_b32 v95, v3, v19 offset0:12 offset1:44
	ds_write2_b32 v176, v4, v20 offset0:160 offset1:192
	ds_write2_b32 v186, v5, v21 offset0:36 offset1:68
	ds_write2_b32 v186, v6, v22 offset0:168 offset1:200
	ds_write2_b32 v187, v7, v23 offset0:44 offset1:76
	ds_write2_b32 v88, v8, v24 offset0:192 offset1:224
	ds_write2_b32 v89, v9, v25 offset0:68 offset1:100
	ds_write2_b32 v89, v10, v26 offset0:200 offset1:232
	ds_write2_b32 v90, v11, v27 offset0:76 offset1:108
	ds_write2_b32 v91, v12, v28 offset0:96 offset1:128
	ds_write2_b32 v191, v13, v29 offset0:100 offset1:132
	ds_write2_b32 v202, v14, v30 offset0:104 offset1:136
	ds_write2_b32 v203, v15, v31 offset0:108 offset1:140
	s_waitcnt lgkmcnt(0)
	s_barrier
	global_load_dwordx4 v[0:3], v[64:65], off
	global_load_dwordx4 v[4:7], v[66:67], off
	global_load_dwordx4 v[8:11], v[68:69], off
	global_load_dwordx4 v[12:15], v[70:71], off
	global_load_dwordx4 v[16:19], v[188:189], off
	global_load_dwordx4 v[20:23], v[192:193], off
	global_load_dwordx4 v[24:27], v[194:195], off
	global_load_dwordx4 v[28:31], v[196:197], off
	ds_read_b128 v[32:35], v190
	ds_read_b128 v[36:39], v190 offset:16
	ds_read_b128 v[40:43], v190 offset:8448
	ds_read_b128 v[44:47], v190 offset:8464
	ds_read_b128 v[48:51], v190 offset:16896
	ds_read_b128 v[52:55], v190 offset:16912
	ds_read_b128 v[56:59], v190 offset:25344
	ds_read_b128 v[60:63], v190 offset:25360
	ds_read_b128 v[64:67], v190 offset:33792
	ds_read_b128 v[68:71], v190 offset:33808
	ds_read_b128 v[72:75], v190 offset:42240
	ds_read_b128 v[76:79], v190 offset:42256
	ds_read_b128 v[80:83], v190 offset:50688
	ds_read_b128 v[84:87], v190 offset:50704
	ds_read_b128 v[88:91], v190 offset:59136
	ds_read_b128 v[92:95], v190 offset:59152
	s_waitcnt lgkmcnt(0)
	s_barrier
; DI float lo_bf(unsigned w) { return __uint_as_float(w << 16); }
; DI float hi_bf(unsigned w) { return __uint_as_float(w & 0xffff0000u); }
; DI void phase_merge(const Params& p, int l, int half, char* smem) {
;     ...
;       for (int ps = 0; ps < 8; ps++) {
;         int row = (tid >> 4) + 16 * ps, ch = tid & 15;
;         const float* s = sC + row * CP + ch * 8;
;         f32x4v a = *(const f32x4v*)s, b = *(const f32x4v*)(s + 4);
;         u32x4 g = *(const u32x4*)(p.G + (mh0 + row) * 4096 + i * 1024 + tn * 128 + ch * 8);
;         y[ps][0] += lo_bf(g.x) * a.x; y[ps][1] += hi_bf(g.x) * a.y; y[ps][2] += lo_bf(g.y) * a.z; y[ps][3] += hi_bf(g.y) * a.w;
;         y[ps][4] += lo_bf(g.z) * b.x; y[ps][5] += hi_bf(g.z) * b.y; y[ps][6] += lo_bf(g.w) * b.z; y[ps][7] += hi_bf(g.w) * b.w;
;       }
;       __syncthreads();
;     }
	s_waitcnt vmcnt(7)
	v_lshlrev_b32_e32 v186, 16, v0
	v_and_b32_e32 v187, 0xffff0000, v0
	v_lshlrev_b32_e32 v0, 16, v1
	v_and_b32_e32 v1, 0xffff0000, v1
	v_lshlrev_b32_e32 v188, 16, v2
	v_and_b32_e32 v189, 0xffff0000, v2
	v_lshlrev_b32_e32 v2, 16, v3
	v_and_b32_e32 v3, 0xffff0000, v3
	s_waitcnt vmcnt(6)
	v_lshlrev_b32_e32 v192, 16, v4
	v_and_b32_e32 v193, 0xffff0000, v4
	v_lshlrev_b32_e32 v4, 16, v5
	v_and_b32_e32 v5, 0xffff0000, v5
	v_lshlrev_b32_e32 v194, 16, v6
	v_and_b32_e32 v195, 0xffff0000, v6
	v_lshlrev_b32_e32 v6, 16, v7
	v_and_b32_e32 v7, 0xffff0000, v7
	s_waitcnt vmcnt(5)
	v_lshlrev_b32_e32 v196, 16, v8
	v_and_b32_e32 v197, 0xffff0000, v8
	v_lshlrev_b32_e32 v8, 16, v9
	v_and_b32_e32 v9, 0xffff0000, v9
	v_lshlrev_b32_e32 v202, 16, v10
	v_and_b32_e32 v203, 0xffff0000, v10
	v_lshlrev_b32_e32 v10, 16, v11
	v_and_b32_e32 v11, 0xffff0000, v11
	s_waitcnt vmcnt(4)
	v_lshlrev_b32_e32 v204, 16, v12
	v_and_b32_e32 v205, 0xffff0000, v12
	v_lshlrev_b32_e32 v12, 16, v13
	v_and_b32_e32 v13, 0xffff0000, v13
	v_lshlrev_b32_e32 v210, 16, v14
	v_and_b32_e32 v211, 0xffff0000, v14
	v_lshlrev_b32_e32 v14, 16, v15
	v_and_b32_e32 v15, 0xffff0000, v15
	s_waitcnt vmcnt(3)
	v_lshlrev_b32_e32 v212, 16, v16
	v_and_b32_e32 v213, 0xffff0000, v16
	v_lshlrev_b32_e32 v16, 16, v17
	v_and_b32_e32 v17, 0xffff0000, v17
	v_lshlrev_b32_e32 v220, 16, v18
	v_and_b32_e32 v221, 0xffff0000, v18
	v_lshlrev_b32_e32 v18, 16, v19
	v_and_b32_e32 v19, 0xffff0000, v19
	s_waitcnt vmcnt(2)
	v_lshlrev_b32_e32 v222, 16, v20
	v_and_b32_e32 v223, 0xffff0000, v20
	v_lshlrev_b32_e32 v20, 16, v21
	v_and_b32_e32 v21, 0xffff0000, v21
	v_lshlrev_b32_e32 v224, 16, v22
	v_and_b32_e32 v225, 0xffff0000, v22
	v_lshlrev_b32_e32 v22, 16, v23
	v_and_b32_e32 v23, 0xffff0000, v23
	s_waitcnt vmcnt(1)
	v_lshlrev_b32_e32 v226, 16, v24
	v_and_b32_e32 v227, 0xffff0000, v24
	v_lshlrev_b32_e32 v24, 16, v25
	v_and_b32_e32 v25, 0xffff0000, v25
	v_lshlrev_b32_e32 v228, 16, v26
	v_and_b32_e32 v229, 0xffff0000, v26
	v_lshlrev_b32_e32 v26, 16, v27
	v_and_b32_e32 v27, 0xffff0000, v27
	s_waitcnt vmcnt(0)
	v_lshlrev_b32_e32 v230, 16, v28
	v_and_b32_e32 v231, 0xffff0000, v28
	v_lshlrev_b32_e32 v28, 16, v29
	v_and_b32_e32 v29, 0xffff0000, v29
	v_lshlrev_b32_e32 v232, 16, v30
	v_and_b32_e32 v233, 0xffff0000, v30
	v_lshlrev_b32_e32 v30, 16, v31
	v_and_b32_e32 v31, 0xffff0000, v31
	v_pk_fma_f32 v[184:185], v[32:33], v[186:187], v[184:185]
	v_pk_fma_f32 v[182:183], v[34:35], v[0:1], v[182:183]
	v_pk_fma_f32 v[180:181], v[36:37], v[188:189], v[180:181]
	v_pk_fma_f32 v[170:171], v[38:39], v[2:3], v[170:171]
	v_pk_fma_f32 v[174:175], v[40:41], v[192:193], v[174:175]
	v_pk_fma_f32 v[172:173], v[42:43], v[4:5], v[172:173]
	v_pk_fma_f32 v[166:167], v[44:45], v[194:195], v[166:167]
	v_pk_fma_f32 v[160:161], v[46:47], v[6:7], v[160:161]
	v_pk_fma_f32 v[168:169], v[48:49], v[196:197], v[168:169]
	v_pk_fma_f32 v[162:163], v[50:51], v[8:9], v[162:163]
	v_pk_fma_f32 v[156:157], v[52:53], v[202:203], v[156:157]
	v_pk_fma_f32 v[152:153], v[54:55], v[10:11], v[152:153]
	v_pk_fma_f32 v[158:159], v[56:57], v[204:205], v[158:159]
	v_pk_fma_f32 v[154:155], v[58:59], v[12:13], v[154:155]
	v_pk_fma_f32 v[148:149], v[60:61], v[210:211], v[148:149]
	v_pk_fma_f32 v[144:145], v[62:63], v[14:15], v[144:145]
	v_pk_fma_f32 v[150:151], v[64:65], v[212:213], v[150:151]
	v_pk_fma_f32 v[146:147], v[66:67], v[16:17], v[146:147]
	v_pk_fma_f32 v[140:141], v[68:69], v[220:221], v[140:141]
	v_pk_fma_f32 v[136:137], v[70:71], v[18:19], v[136:137]
	v_pk_fma_f32 v[142:143], v[72:73], v[222:223], v[142:143]
	v_pk_fma_f32 v[138:139], v[74:75], v[20:21], v[138:139]
	v_pk_fma_f32 v[132:133], v[76:77], v[224:225], v[132:133]
	v_pk_fma_f32 v[128:129], v[78:79], v[22:23], v[128:129]
	v_pk_fma_f32 v[134:135], v[80:81], v[226:227], v[134:135]
	v_pk_fma_f32 v[130:131], v[82:83], v[24:25], v[130:131]
	v_pk_fma_f32 v[124:125], v[84:85], v[228:229], v[124:125]
	v_pk_fma_f32 v[120:121], v[86:87], v[26:27], v[120:121]
	v_pk_fma_f32 v[126:127], v[88:89], v[230:231], v[126:127]
	v_pk_fma_f32 v[122:123], v[90:91], v[28:29], v[122:123]
	v_pk_fma_f32 v[118:119], v[92:93], v[232:233], v[118:119]
	v_pk_fma_f32 v[116:117], v[94:95], v[30:31], v[116:117]
	s_cbranch_scc0 .LBB0_143
; DI void phase_merge(const Params& p, int l, int half, char* smem) {
;     ...
; #pragma unroll
;     for (int ps = 0; ps < 8; ps++) {
;       int row = (tid >> 4) + 16 * ps, ch = tid & 15;
;       *(u32x4*)(p.ybuf + (mh0 + row) * DM + tn * 128 + ch * 8) = pack8(y[ps]);
;     }
;   }
	s_add_u32 s0, s56, s46
	s_addc_u32 s1, s26, s47
	v_lshl_add_u64 v[4:5], s[0:1], 0, v[96:97]
	v_lshl_add_u64 v[6:7], s[0:1], 0, v[98:99]
	v_lshl_add_u64 v[8:9], s[0:1], 0, v[100:101]
	v_lshl_add_u64 v[10:11], s[0:1], 0, v[102:103]
	v_lshl_add_u64 v[12:13], s[0:1], 0, v[104:105]
	v_lshl_add_u64 v[14:15], s[0:1], 0, v[106:107]
	v_lshl_add_u64 v[16:17], s[0:1], 0, v[108:109]
	v_lshl_add_u64 v[18:19], s[0:1], 0, v[110:111]
	v_lshlrev_b64 v[4:5], 11, v[4:5]
	s_bfe_u32 s0, s55, 0x30003
	s_lshl_b32 s0, s0, 8
	v_lshl_add_u64 v[4:5], s[62:63], 0, v[4:5]
	s_and_b32 s26, s0, 0x700
	v_lshl_add_u64 v[4:5], v[4:5], 0, s[26:27]
	v_mov_b32_e32 v115, v177
	v_cvt_pk_bf16_f32 v0, v184, v185
	v_cvt_pk_bf16_f32 v1, v182, v183
	v_cvt_pk_bf16_f32 v2, v180, v181
	v_cvt_pk_bf16_f32 v3, v170, v171
	v_lshl_add_u64 v[4:5], v[4:5], 0, v[114:115]
	global_store_dwordx4 v[4:5], v[0:3], off
	v_lshlrev_b64 v[4:5], 11, v[6:7]
	v_lshl_add_u64 v[4:5], s[62:63], 0, v[4:5]
	v_lshl_add_u64 v[4:5], v[4:5], 0, s[26:27]
	v_cvt_pk_bf16_f32 v0, v174, v175
	v_cvt_pk_bf16_f32 v1, v172, v173
	v_cvt_pk_bf16_f32 v2, v166, v167
	v_cvt_pk_bf16_f32 v3, v160, v161
	v_lshl_add_u64 v[4:5], v[4:5], 0, v[114:115]
	global_store_dwordx4 v[4:5], v[0:3], off
	v_lshlrev_b64 v[4:5], 11, v[8:9]
	v_lshl_add_u64 v[4:5], s[62:63], 0, v[4:5]
	v_lshl_add_u64 v[4:5], v[4:5], 0, s[26:27]
	v_cvt_pk_bf16_f32 v0, v168, v169
	v_cvt_pk_bf16_f32 v1, v162, v163
	v_cvt_pk_bf16_f32 v2, v156, v157
	v_cvt_pk_bf16_f32 v3, v152, v153
	v_lshl_add_u64 v[4:5], v[4:5], 0, v[114:115]
	global_store_dwordx4 v[4:5], v[0:3], off
	v_lshlrev_b64 v[4:5], 11, v[10:11]
	v_lshl_add_u64 v[4:5], s[62:63], 0, v[4:5]
	v_lshl_add_u64 v[4:5], v[4:5], 0, s[26:27]
	v_cvt_pk_bf16_f32 v0, v158, v159
	v_cvt_pk_bf16_f32 v1, v154, v155
	v_cvt_pk_bf16_f32 v2, v148, v149
	v_cvt_pk_bf16_f32 v3, v144, v145
	v_lshl_add_u64 v[4:5], v[4:5], 0, v[114:115]
	global_store_dwordx4 v[4:5], v[0:3], off
	v_lshlrev_b64 v[4:5], 11, v[12:13]
	v_lshl_add_u64 v[4:5], s[62:63], 0, v[4:5]
	v_lshl_add_u64 v[4:5], v[4:5], 0, s[26:27]
	v_cvt_pk_bf16_f32 v0, v150, v151
	v_cvt_pk_bf16_f32 v1, v146, v147
	v_cvt_pk_bf16_f32 v2, v140, v141
	v_cvt_pk_bf16_f32 v3, v136, v137
	v_lshl_add_u64 v[4:5], v[4:5], 0, v[114:115]
	global_store_dwordx4 v[4:5], v[0:3], off
	v_lshlrev_b64 v[4:5], 11, v[14:15]
	v_lshl_add_u64 v[4:5], s[62:63], 0, v[4:5]
	v_lshl_add_u64 v[4:5], v[4:5], 0, s[26:27]
	v_cvt_pk_bf16_f32 v0, v142, v143
	v_cvt_pk_bf16_f32 v1, v138, v139
	v_cvt_pk_bf16_f32 v2, v132, v133
	v_cvt_pk_bf16_f32 v3, v128, v129
	v_lshl_add_u64 v[4:5], v[4:5], 0, v[114:115]
	global_store_dwordx4 v[4:5], v[0:3], off
	v_lshlrev_b64 v[4:5], 11, v[16:17]
	v_lshl_add_u64 v[4:5], s[62:63], 0, v[4:5]
	v_lshl_add_u64 v[4:5], v[4:5], 0, s[26:27]
	v_cvt_pk_bf16_f32 v0, v134, v135
	v_cvt_pk_bf16_f32 v1, v130, v131
	v_cvt_pk_bf16_f32 v2, v124, v125
	v_cvt_pk_bf16_f32 v3, v120, v121
	v_lshl_add_u64 v[4:5], v[4:5], 0, v[114:115]
	global_store_dwordx4 v[4:5], v[0:3], off
	v_lshlrev_b64 v[4:5], 11, v[18:19]
	v_lshl_add_u64 v[4:5], s[62:63], 0, v[4:5]
	v_lshl_add_u64 v[4:5], v[4:5], 0, s[26:27]
	v_cvt_pk_bf16_f32 v0, v126, v127
	v_cvt_pk_bf16_f32 v1, v122, v123
	v_cvt_pk_bf16_f32 v2, v118, v119
	v_cvt_pk_bf16_f32 v3, v116, v117
	v_lshl_add_u64 v[4:5], v[4:5], 0, v[114:115]
	v_readlane_b32 s0, v253, 6
	global_store_dwordx4 v[4:5], v[0:3], off
	v_readlane_b32 s1, v253, 7
	s_load_dword s0, s[0:1], 0x0
	s_waitcnt lgkmcnt(0)
	s_add_i32 s55, s0, s55
	s_cmp_ge_i32 s55, s13
	s_cbranch_scc0 .LBB0_142
